# peel + static priority (waves 4-7) applied to all 9 GEMM K-loops incl. the 5 DFT-GEMM instances
# speedup vs baseline: 1.0061x; 1.0006x over previous
; #define WAIT_V(n) asm volatile("s_waitcnt vmcnt(" #n ")" ::: "memory")
; #define WAIT_L(n) asm volatile("s_waitcnt lgkmcnt(" #n ")" ::: "memory")
; #define BAR __builtin_amdgcn_s_barrier()
; #define SCHED __builtin_amdgcn_sched_barrier(0)
; #define STG_A(b, h, ptr) do { const char* _g = (ptr) + (h) * ahalf; LAS unsigned char* _l = lw + ((b) * 2 + (h)) * 16384; GLDS(_g + voa0, _l); GLDS(_g + voa1, _l + 8192); } while (0)
; #define STG_B(b, h, ptr) do { const char* _g = (ptr) + (h) * bhalf; LAS unsigned char* _l = lw + 65536 + ((b) * 2 + (h)) * 16384; GLDS(_g + vob0, _l); GLDS(_g + vob1, _l + 8192); } while (0)
; #define LDA(dst, b, h) _Pragma("unroll") for (int m = 0; m < 4; ++m) _Pragma("unroll") for (int k = 0; k < 2; ++k) dst[m][k] = *(const LAS bf16x8*)(la + ((b) * 2 + (h)) * 16384 + m * 2048 + k * 1024)
; template <int BMODE, class Epi, class TileFn>
; DEV void gemm_loop(LAS unsigned char* lds, const bf16_t* __restrict__ A, int lda, const bf16_t* __restrict__ B, int ldb, int K, const Epi& epi, int t0, int tstep, int tend, const TileFn& tf) {
;     ...
;     STG_B(0, 0, cB); STG_B(0, 1, cB); STG_A(0, 0, cA); STG_A(0, 1, cA);
;     if (wr == 1) BAR;
;     WAIT_V(2); BAR;
;     STG_B(1, 0, cB + bks); STG_A(1, 0, cA + 128); STG_B(1, 1, cB + bks);
;     WAIT_V(6); BAR;
;     int par = 0;
;     for (int tt = t0;; tt += tstep, par ^= 1) {
;         const bool has_next = tt + tstep < tend;
;         epi.prefetch(lds, brow, par, tid);
;         int nrow = brow, ncol = bcol;
;         if (has_next) tf(tt + tstep, nrow, ncol);
;         const char* nA = (const char*)(A + (size_t)nrow * lda);
;         const char* nB = BMODE == 0 ? (const char*)(B + (size_t)ncol * ldb) : (const char*)(B + (size_t)ncol * 8);
;         for (int t = 0; t < nt; t += 2) {
;             const bool last = (t == nt - 2);
;             const char* a1 = cA + (size_t)(t + 1) * 128;
;             const char* a2 = last ? nA : cA + (size_t)(t + 2) * 128;
;             const char* b2 = last ? nB : cB + (size_t)(t + 2) * bks;
;             const char* a3 = a2 + 128; const char* b3 = b2 + bks;
;             LDB(B0, 0, 0); LDB(B1, 0, 1); SCHED; LDA(At, 0, 0); STG_A(1, 1, a1);
;             WAIT_V(8); WAIT_L(0); BAR; MMA(0, 0, At, B0); MMA(0, 1, At, B1); BAR; SCHED;
.LBB0_647:
	s_or_b64 exec, exec, s[0:1]
	v_lshl_add_u32 v7, v4, 13, 0
	v_lshlrev_b32_e32 v4, 6, v138
	v_and_b32_e32 v5, 15, v138
	v_lshlrev_b32_e32 v6, 2, v138
	v_and_b32_e32 v4, 0x3000, v4
	s_add_i32 s0, 0, 0x10000
	v_add_u32_e32 v147, 0x18000, v139
	v_readlane_b32 s8, v253, 27
	v_lshlrev_b32_e32 v5, 6, v5
	v_and_b32_e32 v6, 32, v6
	v_add_u32_e32 v8, s0, v4
	v_and_b32_e32 v4, 48, v138
	v_readlane_b32 s9, v253, 28
	v_readfirstlane_b32 s0, v147
	v_bitop3_b32 v6, v5, v6, v4 bitop3:0x36
	v_lshl_add_u64 v[4:5], s[8:9], 0, v[194:195]
	s_mov_b32 m0, s0
	v_add_u32_e32 v148, 0x1a000, v139
	s_waitcnt vmcnt(2)
	s_barrier
	global_load_lds_dwordx4 v[4:5], off
	v_lshl_add_u64 v[4:5], s[8:9], 0, v[132:133]
	v_readfirstlane_b32 s0, v148
	v_add_u32_e32 v149, 0x8000, v139
	v_readlane_b32 s8, v253, 16
	v_mov_b32_e32 v129, v195
	s_mov_b32 m0, s0
	v_readlane_b32 s9, v253, 17
	v_readfirstlane_b32 s0, v149
	v_mov_b32_e32 v131, v195
	global_load_lds_dwordx4 v[4:5], off
	v_lshl_add_u64 v[4:5], s[8:9], 0, v[128:129]
	s_mov_b32 m0, s0
	v_add_u32_e32 v150, 0xa000, v139
	global_load_lds_dwordx4 v[4:5], off
	v_lshl_add_u64 v[4:5], s[8:9], 0, v[130:131]
	v_readfirstlane_b32 s0, v150
	v_add_u32_e32 v151, 0x1c000, v139
	v_readlane_b32 s8, v253, 31
	s_mov_b32 m0, s0
	v_readlane_b32 s9, v253, 32
	v_readfirstlane_b32 s0, v151
	v_add_u32_e32 v152, 0x1e000, v139
	global_load_lds_dwordx4 v[4:5], off
	v_lshl_add_u64 v[4:5], s[8:9], 0, v[194:195]
	s_mov_b32 m0, s0
	v_readfirstlane_b32 s0, v152
	global_load_lds_dwordx4 v[4:5], off
	v_lshl_add_u64 v[4:5], s[8:9], 0, v[132:133]
	s_mov_b32 m0, s0
	v_lshrrev_b32_e32 v2, 4, v2
	global_load_lds_dwordx4 v[4:5], off
	s_movk_i32 s0, 0x2800
	v_mul_lo_u32 v2, v2, s0
	v_or_b32_e32 v2, v3, v2
	s_movk_i32 s0, 0x280
	v_mad_u32_u24 v0, v0, s0, v2
	v_add_lshl_u32 v0, v0, v1, 1
	v_mov_b32_e32 v1, v195
	s_waitcnt vmcnt(6)
	v_lshl_add_u64 v[134:135], s[66:67], 0, v[0:1]
	v_add_u32_e32 v0, 0x14000, v0
	v_lshl_add_u64 v[136:137], s[66:67], 0, v[0:1]
	v_readlane_b32 s30, v253, 29
	s_mov_b32 s4, -2
	s_mov_b64 s[0:1], 0x800000
	s_mov_b64 s[36:37], 0x5fc0080
	v_add_u32_e32 v153, v8, v6
	v_add_u32_e32 v154, v7, v6
	v_readlane_b32 s31, v253, 30
	s_barrier
	v_readfirstlane_b32 s100, v188
	s_nop 3
	s_cmp_lt_u32 s100, 0x100
	s_cbranch_scc1 .Lsp_648
	s_setprio 1
.Lsp_648:
	ds_read_b128 v[156:159], v153
	ds_read_b128 v[160:163], v153 offset:1024
	ds_read_b128 v[164:167], v153 offset:2048
	ds_read_b128 v[168:171], v153 offset:3072
	ds_read_b128 v[172:175], v153 offset:16384
	ds_read_b128 v[176:179], v153 offset:17408
	ds_read_b128 v[180:183], v153 offset:18432
	ds_read_b128 v[184:187], v153 offset:19456
	s_add_u32 s7, s36, 0xfa040080
	s_addc_u32 s8, s37, -1
	s_cmp_eq_u32 s4, 6
	s_cselect_b32 s7, 0, s7
	s_cselect_b32 s8, 0, s8
	s_cselect_b32 s9, 0, s0
	s_cselect_b32 s28, 0, s1
	s_add_u32 s38, s68, s7
	s_addc_u32 s39, s69, s8
	s_add_u32 s8, s30, s9
	s_addc_u32 s9, s31, s28
	v_add_u32_e32 v155, 0xc000, v139
	v_lshl_add_u64 v[204:205], v[134:135], 0, s[36:37]
	v_readfirstlane_b32 s7, v155
	v_add_u32_e32 v155, 0xe000, v139
	s_mov_b32 m0, s7
	v_readfirstlane_b32 s7, v155
	ds_read_b128 v[196:199], v154
	ds_read_b128 v[200:203], v154 offset:1024
	ds_read_b128 v[212:215], v154 offset:2048
	ds_read_b128 v[216:219], v154 offset:3072
	ds_read_b128 v[220:223], v154 offset:4096
	ds_read_b128 v[224:227], v154 offset:5120
	ds_read_b128 v[228:231], v154 offset:6144
	ds_read_b128 v[232:235], v154 offset:7168
	global_load_lds_dwordx4 v[204:205], off
	v_lshl_add_u64 v[204:205], v[136:137], 0, s[36:37]
	s_mov_b32 m0, s7
	s_nop 0
	global_load_lds_dwordx4 v[204:205], off
	s_waitcnt vmcnt(8)
	s_waitcnt lgkmcnt(0)
	s_barrier
	s_waitcnt lgkmcnt(0)
	v_mfma_f32_16x16x32_bf16 v[124:127], v[156:159], v[196:199], 0
	v_mfma_f32_16x16x32_bf16 v[120:123], v[164:167], v[196:199], 0
	v_mfma_f32_16x16x32_bf16 v[108:111], v[156:159], v[212:215], 0
	v_mfma_f32_16x16x32_bf16 v[104:107], v[164:167], v[212:215], 0
	v_mfma_f32_16x16x32_bf16 v[92:95], v[156:159], v[220:223], 0
	v_mfma_f32_16x16x32_bf16 v[88:91], v[164:167], v[220:223], 0
	v_mfma_f32_16x16x32_bf16 v[76:79], v[156:159], v[228:231], 0
	v_mfma_f32_16x16x32_bf16 v[72:75], v[164:167], v[228:231], 0
	v_mfma_f32_16x16x32_bf16 v[124:127], v[160:163], v[200:203], v[124:127]
	v_mfma_f32_16x16x32_bf16 v[120:123], v[168:171], v[200:203], v[120:123]
	v_mfma_f32_16x16x32_bf16 v[108:111], v[160:163], v[216:219], v[108:111]
	v_mfma_f32_16x16x32_bf16 v[104:107], v[168:171], v[216:219], v[104:107]
	v_mfma_f32_16x16x32_bf16 v[92:95], v[160:163], v[224:227], v[92:95]
	v_mfma_f32_16x16x32_bf16 v[88:91], v[168:171], v[224:227], v[88:91]
	v_mfma_f32_16x16x32_bf16 v[76:79], v[160:163], v[232:235], v[76:79]
	v_mfma_f32_16x16x32_bf16 v[72:75], v[168:171], v[232:235], v[72:75]
	v_mfma_f32_16x16x32_bf16 v[116:119], v[172:175], v[196:199], 0
	v_mfma_f32_16x16x32_bf16 v[112:115], v[180:183], v[196:199], 0
	v_mfma_f32_16x16x32_bf16 v[100:103], v[172:175], v[212:215], 0
	v_mfma_f32_16x16x32_bf16 v[96:99], v[180:183], v[212:215], 0
	v_mfma_f32_16x16x32_bf16 v[84:87], v[172:175], v[220:223], 0
	v_mfma_f32_16x16x32_bf16 v[80:83], v[180:183], v[220:223], 0
	v_mfma_f32_16x16x32_bf16 v[68:71], v[172:175], v[228:231], 0
	v_mfma_f32_16x16x32_bf16 v[64:67], v[180:183], v[228:231], 0
	v_mfma_f32_16x16x32_bf16 v[116:119], v[176:179], v[200:203], v[116:119]
	v_mfma_f32_16x16x32_bf16 v[112:115], v[184:187], v[200:203], v[112:115]
	v_mfma_f32_16x16x32_bf16 v[100:103], v[176:179], v[216:219], v[100:103]
	v_mfma_f32_16x16x32_bf16 v[96:99], v[184:187], v[216:219], v[96:99]
	v_mfma_f32_16x16x32_bf16 v[84:87], v[176:179], v[224:227], v[84:87]
	v_mfma_f32_16x16x32_bf16 v[80:83], v[184:187], v[224:227], v[80:83]
	v_mfma_f32_16x16x32_bf16 v[68:71], v[176:179], v[232:235], v[68:71]
	v_mfma_f32_16x16x32_bf16 v[64:67], v[184:187], v[232:235], v[64:67]
	s_barrier
; #define WAIT_V(n) asm volatile("s_waitcnt vmcnt(" #n ")" ::: "memory")
; #define WAIT_L(n) asm volatile("s_waitcnt lgkmcnt(" #n ")" ::: "memory")
; #define BAR __builtin_amdgcn_s_barrier()
; #define SCHED __builtin_amdgcn_sched_barrier(0)
; #define STG_A(b, h, ptr) do { const char* _g = (ptr) + (h) * ahalf; LAS unsigned char* _l = lw + ((b) * 2 + (h)) * 16384; GLDS(_g + voa0, _l); GLDS(_g + voa1, _l + 8192); } while (0)
; #define STG_B(b, h, ptr) do { const char* _g = (ptr) + (h) * bhalf; LAS unsigned char* _l = lw + 65536 + ((b) * 2 + (h)) * 16384; GLDS(_g + vob0, _l); GLDS(_g + vob1, _l + 8192); } while (0)
; #define LDA(dst, b, h) _Pragma("unroll") for (int m = 0; m < 4; ++m) _Pragma("unroll") for (int k = 0; k < 2; ++k) dst[m][k] = *(const LAS bf16x8*)(la + ((b) * 2 + (h)) * 16384 + m * 2048 + k * 1024)
; #define LDB(dst, b, h) _Pragma("unroll") for (int n = 0; n < 2; ++n) _Pragma("unroll") for (int k = 0; k < 2; ++k) dst[n][k] = *(const LAS bf16x8*)(lb + ((b) * 2 + (h)) * 16384 + n * 2048 + k * 1024)
; #define MMA(ai, bj, Af, Bf) do { __builtin_amdgcn_s_setprio(1); \
;     _Pragma("unroll") for (int m = 0; m < 4; ++m) _Pragma("unroll") for (int n = 0; n < 2; ++n) _Pragma("unroll") for (int k = 0; k < 2; ++k) \
;         acc[ai][bj][m][n] = __builtin_amdgcn_mfma_f32_16x16x32_bf16(Bf[n][k], Af[m][k], acc[ai][bj][m][n], 0, 0, 0); \
;     __builtin_amdgcn_s_setprio(0); } while (0)
; template <int BMODE, class Epi, class TileFn>
; DEV void gemm_loop(LAS unsigned char* lds, const bf16_t* __restrict__ A, int lda, const bf16_t* __restrict__ B, int ldb, int K, const Epi& epi, int t0, int tstep, int tend, const TileFn& tf) {
;     ...
;             LDB(B0, 0, 0); LDB(B1, 0, 1); SCHED; LDA(At, 0, 0); STG_A(1, 1, a1);
;             WAIT_V(8); WAIT_L(0); BAR; MMA(0, 0, At, B0); MMA(0, 1, At, B1); BAR; SCHED;
;             LDA(At, 0, 1); STG_B(0, 0, b2); STG_B(0, 1, b2); STG_A(0, 0, a2);
;             WAIT_V(8); WAIT_L(0); BAR; MMA(1, 0, At, B0); MMA(1, 1, At, B1); BAR; SCHED;
;             LDB(B0, 1, 0); LDB(B1, 1, 1); SCHED; LDA(At, 1, 0); STG_A(0, 1, a2);
	v_readfirstlane_b32 s7, v140
	v_lshl_add_u64 v[204:205], s[8:9], 0, v[194:195]
	s_mov_b32 m0, s7
	v_readfirstlane_b32 s7, v141
	ds_read_b128 v[196:199], v154 offset:16384
	ds_read_b128 v[200:203], v154 offset:17408
	ds_read_b128 v[212:215], v154 offset:18432
	ds_read_b128 v[216:219], v154 offset:19456
	ds_read_b128 v[220:223], v154 offset:20480
	ds_read_b128 v[224:227], v154 offset:21504
	ds_read_b128 v[228:231], v154 offset:22528
	ds_read_b128 v[232:235], v154 offset:23552
	global_load_lds_dwordx4 v[204:205], off
	v_lshl_add_u64 v[236:237], s[8:9], 0, v[132:133]
	s_mov_b32 m0, s7
	v_readfirstlane_b32 s7, v142
	global_load_lds_dwordx4 v[236:237], off
	v_lshl_add_u64 v[204:205], v[204:205], 0, s[86:87]
	s_mov_b32 m0, s7
	v_readfirstlane_b32 s7, v143
	global_load_lds_dwordx4 v[204:205], off
	v_lshl_add_u64 v[204:205], v[236:237], 0, s[86:87]
	s_mov_b32 m0, s7
	v_readfirstlane_b32 s7, v139
	global_load_lds_dwordx4 v[204:205], off
	v_lshl_add_u64 v[204:205], s[38:39], 0, v[128:129]
	s_mov_b32 m0, s7
	v_readfirstlane_b32 s7, v144
	global_load_lds_dwordx4 v[204:205], off
	v_lshl_add_u64 v[236:237], s[38:39], 0, v[130:131]
	s_mov_b32 m0, s7
	s_nop 0
	global_load_lds_dwordx4 v[236:237], off
	s_waitcnt vmcnt(8)
	s_waitcnt lgkmcnt(0)
	s_barrier
	s_waitcnt lgkmcnt(0)
	v_mfma_f32_16x16x32_bf16 v[60:63], v[156:159], v[196:199], 0
	v_mfma_f32_16x16x32_bf16 v[56:59], v[164:167], v[196:199], 0
	v_mfma_f32_16x16x32_bf16 v[44:47], v[156:159], v[212:215], 0
	v_mfma_f32_16x16x32_bf16 v[40:43], v[164:167], v[212:215], 0
	v_mfma_f32_16x16x32_bf16 v[28:31], v[156:159], v[220:223], 0
	v_mfma_f32_16x16x32_bf16 v[24:27], v[164:167], v[220:223], 0
	v_mfma_f32_16x16x32_bf16 v[12:15], v[156:159], v[228:231], 0
	v_mfma_f32_16x16x32_bf16 v[8:11], v[164:167], v[228:231], 0
	v_mfma_f32_16x16x32_bf16 v[60:63], v[160:163], v[200:203], v[60:63]
	v_mfma_f32_16x16x32_bf16 v[56:59], v[168:171], v[200:203], v[56:59]
	v_mfma_f32_16x16x32_bf16 v[44:47], v[160:163], v[216:219], v[44:47]
	v_mfma_f32_16x16x32_bf16 v[40:43], v[168:171], v[216:219], v[40:43]
	v_mfma_f32_16x16x32_bf16 v[28:31], v[160:163], v[224:227], v[28:31]
	v_mfma_f32_16x16x32_bf16 v[24:27], v[168:171], v[224:227], v[24:27]
	v_mfma_f32_16x16x32_bf16 v[12:15], v[160:163], v[232:235], v[12:15]
	v_mfma_f32_16x16x32_bf16 v[8:11], v[168:171], v[232:235], v[8:11]
	v_mfma_f32_16x16x32_bf16 v[52:55], v[172:175], v[196:199], 0
	v_mfma_f32_16x16x32_bf16 v[48:51], v[180:183], v[196:199], 0
	v_mfma_f32_16x16x32_bf16 v[36:39], v[172:175], v[212:215], 0
	v_mfma_f32_16x16x32_bf16 v[32:35], v[180:183], v[212:215], 0
	v_mfma_f32_16x16x32_bf16 v[20:23], v[172:175], v[220:223], 0
	v_mfma_f32_16x16x32_bf16 v[16:19], v[180:183], v[220:223], 0
	v_mfma_f32_16x16x32_bf16 v[4:7], v[172:175], v[228:231], 0
	v_mfma_f32_16x16x32_bf16 v[0:3], v[180:183], v[228:231], 0
	v_mfma_f32_16x16x32_bf16 v[52:55], v[176:179], v[200:203], v[52:55]
	v_mfma_f32_16x16x32_bf16 v[48:51], v[184:187], v[200:203], v[48:51]
	v_mfma_f32_16x16x32_bf16 v[36:39], v[176:179], v[216:219], v[36:39]
	v_mfma_f32_16x16x32_bf16 v[32:35], v[184:187], v[216:219], v[32:35]
	v_mfma_f32_16x16x32_bf16 v[20:23], v[176:179], v[224:227], v[20:23]
	v_mfma_f32_16x16x32_bf16 v[16:19], v[184:187], v[224:227], v[16:19]
	v_mfma_f32_16x16x32_bf16 v[4:7], v[176:179], v[232:235], v[4:7]
	v_mfma_f32_16x16x32_bf16 v[0:3], v[184:187], v[232:235], v[0:3]
	s_barrier
	s_branch .Lkmid_648
.LBB0_648:
	ds_read_b128 v[156:159], v153
	ds_read_b128 v[160:163], v153 offset:1024
	ds_read_b128 v[164:167], v153 offset:2048
	ds_read_b128 v[168:171], v153 offset:3072
	ds_read_b128 v[172:175], v153 offset:16384
	ds_read_b128 v[176:179], v153 offset:17408
	ds_read_b128 v[180:183], v153 offset:18432
	ds_read_b128 v[184:187], v153 offset:19456
	s_add_u32 s7, s36, 0xfa040080
	s_addc_u32 s8, s37, -1
	s_cmp_eq_u32 s4, 6
	s_cselect_b32 s7, 0, s7
	s_cselect_b32 s8, 0, s8
	s_cselect_b32 s9, 0, s0
	s_cselect_b32 s28, 0, s1
	s_add_u32 s38, s68, s7
	s_addc_u32 s39, s69, s8
	s_add_u32 s8, s30, s9
	s_addc_u32 s9, s31, s28
	v_add_u32_e32 v155, 0xc000, v139
	v_lshl_add_u64 v[204:205], v[134:135], 0, s[36:37]
	v_readfirstlane_b32 s7, v155
	v_add_u32_e32 v155, 0xe000, v139
	s_mov_b32 m0, s7
	v_readfirstlane_b32 s7, v155
	ds_read_b128 v[196:199], v154
	ds_read_b128 v[200:203], v154 offset:1024
	ds_read_b128 v[212:215], v154 offset:2048
	ds_read_b128 v[216:219], v154 offset:3072
	ds_read_b128 v[220:223], v154 offset:4096
	ds_read_b128 v[224:227], v154 offset:5120
	ds_read_b128 v[228:231], v154 offset:6144
	ds_read_b128 v[232:235], v154 offset:7168
	global_load_lds_dwordx4 v[204:205], off
	v_lshl_add_u64 v[204:205], v[136:137], 0, s[36:37]
	s_mov_b32 m0, s7
	s_nop 0
	global_load_lds_dwordx4 v[204:205], off
	s_waitcnt vmcnt(8)
	s_waitcnt lgkmcnt(0)
	s_barrier
; #define WAIT_V(n) asm volatile("s_waitcnt vmcnt(" #n ")" ::: "memory")
; #define WAIT_L(n) asm volatile("s_waitcnt lgkmcnt(" #n ")" ::: "memory")
; #define BAR __builtin_amdgcn_s_barrier()
; #define SCHED __builtin_amdgcn_sched_barrier(0)
; #define STG_A(b, h, ptr) do { const char* _g = (ptr) + (h) * ahalf; LAS unsigned char* _l = lw + ((b) * 2 + (h)) * 16384; GLDS(_g + voa0, _l); GLDS(_g + voa1, _l + 8192); } while (0)
; #define STG_B(b, h, ptr) do { const char* _g = (ptr) + (h) * bhalf; LAS unsigned char* _l = lw + 65536 + ((b) * 2 + (h)) * 16384; GLDS(_g + vob0, _l); GLDS(_g + vob1, _l + 8192); } while (0)
; #define LDA(dst, b, h) _Pragma("unroll") for (int m = 0; m < 4; ++m) _Pragma("unroll") for (int k = 0; k < 2; ++k) dst[m][k] = *(const LAS bf16x8*)(la + ((b) * 2 + (h)) * 16384 + m * 2048 + k * 1024)
; #define LDB(dst, b, h) _Pragma("unroll") for (int n = 0; n < 2; ++n) _Pragma("unroll") for (int k = 0; k < 2; ++k) dst[n][k] = *(const LAS bf16x8*)(lb + ((b) * 2 + (h)) * 16384 + n * 2048 + k * 1024)
; #define MMA(ai, bj, Af, Bf) do { __builtin_amdgcn_s_setprio(1); \
;     _Pragma("unroll") for (int m = 0; m < 4; ++m) _Pragma("unroll") for (int n = 0; n < 2; ++n) _Pragma("unroll") for (int k = 0; k < 2; ++k) \
;         acc[ai][bj][m][n] = __builtin_amdgcn_mfma_f32_16x16x32_bf16(Bf[n][k], Af[m][k], acc[ai][bj][m][n], 0, 0, 0); \
;     __builtin_amdgcn_s_setprio(0); } while (0)
; template <int BMODE, class Epi, class TileFn>
; DEV void gemm_loop(LAS unsigned char* lds, const bf16_t* __restrict__ A, int lda, const bf16_t* __restrict__ B, int ldb, int K, const Epi& epi, int t0, int tstep, int tend, const TileFn& tf) {
;     ...
;             WAIT_V(8); WAIT_L(0); BAR; MMA(0, 0, At, B0); MMA(0, 1, At, B1); BAR; SCHED;
;             LDA(At, 0, 1); STG_B(0, 0, b2); STG_B(0, 1, b2); STG_A(0, 0, a2);
;             WAIT_V(8); WAIT_L(0); BAR; MMA(1, 0, At, B0); MMA(1, 1, At, B1); BAR; SCHED;
;             LDB(B0, 1, 0); LDB(B1, 1, 1); SCHED; LDA(At, 1, 0); STG_A(0, 1, a2);
;             WAIT_V(8); WAIT_L(0); BAR; MMA(0, 0, At, B0); MMA(0, 1, At, B1); BAR; SCHED;
;             LDA(At, 1, 1); STG_B(1, 0, b3); STG_B(1, 1, b3); STG_A(1, 0, a3);
;             WAIT_V(8); WAIT_L(0); BAR; MMA(1, 0, At, B0); MMA(1, 1, At, B1); BAR; SCHED;
	s_waitcnt lgkmcnt(0)
	v_mfma_f32_16x16x32_bf16 v[124:127], v[156:159], v[196:199], v[124:127]
	v_mfma_f32_16x16x32_bf16 v[120:123], v[164:167], v[196:199], v[120:123]
	v_mfma_f32_16x16x32_bf16 v[108:111], v[156:159], v[212:215], v[108:111]
	v_mfma_f32_16x16x32_bf16 v[104:107], v[164:167], v[212:215], v[104:107]
	v_mfma_f32_16x16x32_bf16 v[92:95], v[156:159], v[220:223], v[92:95]
	v_mfma_f32_16x16x32_bf16 v[88:91], v[164:167], v[220:223], v[88:91]
	v_mfma_f32_16x16x32_bf16 v[76:79], v[156:159], v[228:231], v[76:79]
	v_mfma_f32_16x16x32_bf16 v[72:75], v[164:167], v[228:231], v[72:75]
	v_mfma_f32_16x16x32_bf16 v[124:127], v[160:163], v[200:203], v[124:127]
	v_mfma_f32_16x16x32_bf16 v[120:123], v[168:171], v[200:203], v[120:123]
	v_mfma_f32_16x16x32_bf16 v[108:111], v[160:163], v[216:219], v[108:111]
	v_mfma_f32_16x16x32_bf16 v[104:107], v[168:171], v[216:219], v[104:107]
	v_mfma_f32_16x16x32_bf16 v[92:95], v[160:163], v[224:227], v[92:95]
	v_mfma_f32_16x16x32_bf16 v[88:91], v[168:171], v[224:227], v[88:91]
	v_mfma_f32_16x16x32_bf16 v[76:79], v[160:163], v[232:235], v[76:79]
	v_mfma_f32_16x16x32_bf16 v[72:75], v[168:171], v[232:235], v[72:75]
	v_mfma_f32_16x16x32_bf16 v[116:119], v[172:175], v[196:199], v[116:119]
	v_mfma_f32_16x16x32_bf16 v[112:115], v[180:183], v[196:199], v[112:115]
	v_mfma_f32_16x16x32_bf16 v[100:103], v[172:175], v[212:215], v[100:103]
	v_mfma_f32_16x16x32_bf16 v[96:99], v[180:183], v[212:215], v[96:99]
	v_mfma_f32_16x16x32_bf16 v[84:87], v[172:175], v[220:223], v[84:87]
	v_mfma_f32_16x16x32_bf16 v[80:83], v[180:183], v[220:223], v[80:83]
	v_mfma_f32_16x16x32_bf16 v[68:71], v[172:175], v[228:231], v[68:71]
	v_mfma_f32_16x16x32_bf16 v[64:67], v[180:183], v[228:231], v[64:67]
	v_mfma_f32_16x16x32_bf16 v[116:119], v[176:179], v[200:203], v[116:119]
	v_mfma_f32_16x16x32_bf16 v[112:115], v[184:187], v[200:203], v[112:115]
	v_mfma_f32_16x16x32_bf16 v[100:103], v[176:179], v[216:219], v[100:103]
	v_mfma_f32_16x16x32_bf16 v[96:99], v[184:187], v[216:219], v[96:99]
	v_mfma_f32_16x16x32_bf16 v[84:87], v[176:179], v[224:227], v[84:87]
	v_mfma_f32_16x16x32_bf16 v[80:83], v[184:187], v[224:227], v[80:83]
	v_mfma_f32_16x16x32_bf16 v[68:71], v[176:179], v[232:235], v[68:71]
	v_mfma_f32_16x16x32_bf16 v[64:67], v[184:187], v[232:235], v[64:67]
	s_barrier
	v_readfirstlane_b32 s7, v140
	v_lshl_add_u64 v[204:205], s[8:9], 0, v[194:195]
	s_mov_b32 m0, s7
	v_readfirstlane_b32 s7, v141
	ds_read_b128 v[196:199], v154 offset:16384
	ds_read_b128 v[200:203], v154 offset:17408
	ds_read_b128 v[212:215], v154 offset:18432
	ds_read_b128 v[216:219], v154 offset:19456
	ds_read_b128 v[220:223], v154 offset:20480
	ds_read_b128 v[224:227], v154 offset:21504
	ds_read_b128 v[228:231], v154 offset:22528
	ds_read_b128 v[232:235], v154 offset:23552
	global_load_lds_dwordx4 v[204:205], off
	v_lshl_add_u64 v[236:237], s[8:9], 0, v[132:133]
	s_mov_b32 m0, s7
	v_readfirstlane_b32 s7, v142
	global_load_lds_dwordx4 v[236:237], off
	v_lshl_add_u64 v[204:205], v[204:205], 0, s[86:87]
	s_mov_b32 m0, s7
	v_readfirstlane_b32 s7, v143
	global_load_lds_dwordx4 v[204:205], off
	v_lshl_add_u64 v[204:205], v[236:237], 0, s[86:87]
	s_mov_b32 m0, s7
	v_readfirstlane_b32 s7, v139
	global_load_lds_dwordx4 v[204:205], off
	v_lshl_add_u64 v[204:205], s[38:39], 0, v[128:129]
	s_mov_b32 m0, s7
	v_readfirstlane_b32 s7, v144
	global_load_lds_dwordx4 v[204:205], off
	v_lshl_add_u64 v[236:237], s[38:39], 0, v[130:131]
	s_mov_b32 m0, s7
	s_nop 0
	global_load_lds_dwordx4 v[236:237], off
	s_waitcnt vmcnt(8)
	s_waitcnt lgkmcnt(0)
	s_barrier
	s_waitcnt lgkmcnt(0)
	v_mfma_f32_16x16x32_bf16 v[60:63], v[156:159], v[196:199], v[60:63]
	v_mfma_f32_16x16x32_bf16 v[56:59], v[164:167], v[196:199], v[56:59]
	v_mfma_f32_16x16x32_bf16 v[44:47], v[156:159], v[212:215], v[44:47]
	v_mfma_f32_16x16x32_bf16 v[40:43], v[164:167], v[212:215], v[40:43]
	v_mfma_f32_16x16x32_bf16 v[28:31], v[156:159], v[220:223], v[28:31]
	v_mfma_f32_16x16x32_bf16 v[24:27], v[164:167], v[220:223], v[24:27]
	v_mfma_f32_16x16x32_bf16 v[12:15], v[156:159], v[228:231], v[12:15]
	v_mfma_f32_16x16x32_bf16 v[8:11], v[164:167], v[228:231], v[8:11]
	v_mfma_f32_16x16x32_bf16 v[60:63], v[160:163], v[200:203], v[60:63]
	v_mfma_f32_16x16x32_bf16 v[56:59], v[168:171], v[200:203], v[56:59]
	v_mfma_f32_16x16x32_bf16 v[44:47], v[160:163], v[216:219], v[44:47]
	v_mfma_f32_16x16x32_bf16 v[40:43], v[168:171], v[216:219], v[40:43]
	v_mfma_f32_16x16x32_bf16 v[28:31], v[160:163], v[224:227], v[28:31]
	v_mfma_f32_16x16x32_bf16 v[24:27], v[168:171], v[224:227], v[24:27]
	v_mfma_f32_16x16x32_bf16 v[12:15], v[160:163], v[232:235], v[12:15]
	v_mfma_f32_16x16x32_bf16 v[8:11], v[168:171], v[232:235], v[8:11]
	v_mfma_f32_16x16x32_bf16 v[52:55], v[172:175], v[196:199], v[52:55]
	v_mfma_f32_16x16x32_bf16 v[48:51], v[180:183], v[196:199], v[48:51]
	v_mfma_f32_16x16x32_bf16 v[36:39], v[172:175], v[212:215], v[36:39]
	v_mfma_f32_16x16x32_bf16 v[32:35], v[180:183], v[212:215], v[32:35]
	v_mfma_f32_16x16x32_bf16 v[20:23], v[172:175], v[220:223], v[20:23]
	v_mfma_f32_16x16x32_bf16 v[16:19], v[180:183], v[220:223], v[16:19]
	v_mfma_f32_16x16x32_bf16 v[4:7], v[172:175], v[228:231], v[4:7]
	v_mfma_f32_16x16x32_bf16 v[0:3], v[180:183], v[228:231], v[0:3]
	v_mfma_f32_16x16x32_bf16 v[52:55], v[176:179], v[200:203], v[52:55]
	v_mfma_f32_16x16x32_bf16 v[48:51], v[184:187], v[200:203], v[48:51]
	v_mfma_f32_16x16x32_bf16 v[36:39], v[176:179], v[216:219], v[36:39]
	v_mfma_f32_16x16x32_bf16 v[32:35], v[184:187], v[216:219], v[32:35]
	v_mfma_f32_16x16x32_bf16 v[20:23], v[176:179], v[224:227], v[20:23]
	v_mfma_f32_16x16x32_bf16 v[16:19], v[184:187], v[224:227], v[16:19]
	v_mfma_f32_16x16x32_bf16 v[4:7], v[176:179], v[232:235], v[4:7]
	v_mfma_f32_16x16x32_bf16 v[0:3], v[184:187], v[232:235], v[0:3]
	s_barrier
; #define WAIT_V(n) asm volatile("s_waitcnt vmcnt(" #n ")" ::: "memory")
; #define WAIT_L(n) asm volatile("s_waitcnt lgkmcnt(" #n ")" ::: "memory")
; #define BAR __builtin_amdgcn_s_barrier()
; #define SCHED __builtin_amdgcn_sched_barrier(0)
; #define STG_A(b, h, ptr) do { const char* _g = (ptr) + (h) * ahalf; LAS unsigned char* _l = lw + ((b) * 2 + (h)) * 16384; GLDS(_g + voa0, _l); GLDS(_g + voa1, _l + 8192); } while (0)
; #define LDA(dst, b, h) _Pragma("unroll") for (int m = 0; m < 4; ++m) _Pragma("unroll") for (int k = 0; k < 2; ++k) dst[m][k] = *(const LAS bf16x8*)(la + ((b) * 2 + (h)) * 16384 + m * 2048 + k * 1024)
; #define LDB(dst, b, h) _Pragma("unroll") for (int n = 0; n < 2; ++n) _Pragma("unroll") for (int k = 0; k < 2; ++k) dst[n][k] = *(const LAS bf16x8*)(lb + ((b) * 2 + (h)) * 16384 + n * 2048 + k * 1024)
; #define MMA(ai, bj, Af, Bf) do { __builtin_amdgcn_s_setprio(1); \
;     _Pragma("unroll") for (int m = 0; m < 4; ++m) _Pragma("unroll") for (int n = 0; n < 2; ++n) _Pragma("unroll") for (int k = 0; k < 2; ++k) \
;         acc[ai][bj][m][n] = __builtin_amdgcn_mfma_f32_16x16x32_bf16(Bf[n][k], Af[m][k], acc[ai][bj][m][n], 0, 0, 0); \
;     __builtin_amdgcn_s_setprio(0); } while (0)
; template <int BMODE, class Epi, class TileFn>
; DEV void gemm_loop(LAS unsigned char* lds, const bf16_t* __restrict__ A, int lda, const bf16_t* __restrict__ B, int ldb, int K, const Epi& epi, int t0, int tstep, int tend, const TileFn& tf) {
;     ...
;             LDB(B0, 1, 0); LDB(B1, 1, 1); SCHED; LDA(At, 1, 0); STG_A(0, 1, a2);
;             WAIT_V(8); WAIT_L(0); BAR; MMA(0, 0, At, B0); MMA(0, 1, At, B1); BAR; SCHED;
.Lkmid_648:
	ds_read_b128 v[156:159], v153 offset:32768
	ds_read_b128 v[160:163], v153 offset:33792
	ds_read_b128 v[164:167], v153 offset:34816
	ds_read_b128 v[168:171], v153 offset:35840
	ds_read_b128 v[172:175], v153 offset:49152
	ds_read_b128 v[176:179], v153 offset:50176
	ds_read_b128 v[180:183], v153 offset:51200
	ds_read_b128 v[184:187], v153 offset:52224
	s_add_u32 s28, s38, 0x28000
	s_addc_u32 s29, s39, 0
	v_readfirstlane_b32 s7, v145
	v_lshl_add_u64 v[238:239], s[28:29], 0, v[128:129]
	s_mov_b32 m0, s7
	v_readfirstlane_b32 s7, v146
	ds_read_b128 v[196:199], v154 offset:32768
	ds_read_b128 v[200:203], v154 offset:33792
	ds_read_b128 v[212:215], v154 offset:34816
	ds_read_b128 v[216:219], v154 offset:35840
	ds_read_b128 v[220:223], v154 offset:36864
	ds_read_b128 v[224:227], v154 offset:37888
	ds_read_b128 v[228:231], v154 offset:38912
	ds_read_b128 v[232:235], v154 offset:39936
	global_load_lds_dwordx4 v[238:239], off
	v_lshl_add_u64 v[238:239], s[28:29], 0, v[130:131]
	s_mov_b32 m0, s7
	s_nop 0
	global_load_lds_dwordx4 v[238:239], off
	s_waitcnt vmcnt(8)
	s_waitcnt lgkmcnt(0)
	s_barrier
	s_waitcnt lgkmcnt(0)
	v_mfma_f32_16x16x32_bf16 v[124:127], v[156:159], v[196:199], v[124:127]
	v_mfma_f32_16x16x32_bf16 v[120:123], v[164:167], v[196:199], v[120:123]
	v_mfma_f32_16x16x32_bf16 v[108:111], v[156:159], v[212:215], v[108:111]
	v_mfma_f32_16x16x32_bf16 v[104:107], v[164:167], v[212:215], v[104:107]
	v_mfma_f32_16x16x32_bf16 v[92:95], v[156:159], v[220:223], v[92:95]
	v_mfma_f32_16x16x32_bf16 v[88:91], v[164:167], v[220:223], v[88:91]
	v_mfma_f32_16x16x32_bf16 v[76:79], v[156:159], v[228:231], v[76:79]
	v_mfma_f32_16x16x32_bf16 v[72:75], v[164:167], v[228:231], v[72:75]
	v_mfma_f32_16x16x32_bf16 v[124:127], v[160:163], v[200:203], v[124:127]
	v_mfma_f32_16x16x32_bf16 v[120:123], v[168:171], v[200:203], v[120:123]
	v_mfma_f32_16x16x32_bf16 v[108:111], v[160:163], v[216:219], v[108:111]
	v_mfma_f32_16x16x32_bf16 v[104:107], v[168:171], v[216:219], v[104:107]
	v_mfma_f32_16x16x32_bf16 v[92:95], v[160:163], v[224:227], v[92:95]
	v_mfma_f32_16x16x32_bf16 v[88:91], v[168:171], v[224:227], v[88:91]
	v_mfma_f32_16x16x32_bf16 v[76:79], v[160:163], v[232:235], v[76:79]
	v_mfma_f32_16x16x32_bf16 v[72:75], v[168:171], v[232:235], v[72:75]
	v_mfma_f32_16x16x32_bf16 v[116:119], v[172:175], v[196:199], v[116:119]
	v_mfma_f32_16x16x32_bf16 v[112:115], v[180:183], v[196:199], v[112:115]
	v_mfma_f32_16x16x32_bf16 v[100:103], v[172:175], v[212:215], v[100:103]
	v_mfma_f32_16x16x32_bf16 v[96:99], v[180:183], v[212:215], v[96:99]
	v_mfma_f32_16x16x32_bf16 v[84:87], v[172:175], v[220:223], v[84:87]
	v_mfma_f32_16x16x32_bf16 v[80:83], v[180:183], v[220:223], v[80:83]
	v_mfma_f32_16x16x32_bf16 v[68:71], v[172:175], v[228:231], v[68:71]
	v_mfma_f32_16x16x32_bf16 v[64:67], v[180:183], v[228:231], v[64:67]
	v_mfma_f32_16x16x32_bf16 v[116:119], v[176:179], v[200:203], v[116:119]
	v_mfma_f32_16x16x32_bf16 v[112:115], v[184:187], v[200:203], v[112:115]
	v_mfma_f32_16x16x32_bf16 v[100:103], v[176:179], v[216:219], v[100:103]
	v_mfma_f32_16x16x32_bf16 v[96:99], v[184:187], v[216:219], v[96:99]
	v_mfma_f32_16x16x32_bf16 v[84:87], v[176:179], v[224:227], v[84:87]
	v_mfma_f32_16x16x32_bf16 v[80:83], v[184:187], v[224:227], v[80:83]
	v_mfma_f32_16x16x32_bf16 v[68:71], v[176:179], v[232:235], v[68:71]
	v_mfma_f32_16x16x32_bf16 v[64:67], v[184:187], v[232:235], v[64:67]
	s_barrier
; #define WAIT_V(n) asm volatile("s_waitcnt vmcnt(" #n ")" ::: "memory")
; #define WAIT_L(n) asm volatile("s_waitcnt lgkmcnt(" #n ")" ::: "memory")
; #define BAR __builtin_amdgcn_s_barrier()
; #define SCHED __builtin_amdgcn_sched_barrier(0)
; #define STG_A(b, h, ptr) do { const char* _g = (ptr) + (h) * ahalf; LAS unsigned char* _l = lw + ((b) * 2 + (h)) * 16384; GLDS(_g + voa0, _l); GLDS(_g + voa1, _l + 8192); } while (0)
; #define STG_B(b, h, ptr) do { const char* _g = (ptr) + (h) * bhalf; LAS unsigned char* _l = lw + 65536 + ((b) * 2 + (h)) * 16384; GLDS(_g + vob0, _l); GLDS(_g + vob1, _l + 8192); } while (0)
; #define LDA(dst, b, h) _Pragma("unroll") for (int m = 0; m < 4; ++m) _Pragma("unroll") for (int k = 0; k < 2; ++k) dst[m][k] = *(const LAS bf16x8*)(la + ((b) * 2 + (h)) * 16384 + m * 2048 + k * 1024)
; #define MMA(ai, bj, Af, Bf) do { __builtin_amdgcn_s_setprio(1); \
;     _Pragma("unroll") for (int m = 0; m < 4; ++m) _Pragma("unroll") for (int n = 0; n < 2; ++n) _Pragma("unroll") for (int k = 0; k < 2; ++k) \
;         acc[ai][bj][m][n] = __builtin_amdgcn_mfma_f32_16x16x32_bf16(Bf[n][k], Af[m][k], acc[ai][bj][m][n], 0, 0, 0); \
;     __builtin_amdgcn_s_setprio(0); } while (0)
; template <int BMODE, class Epi, class TileFn>
; DEV void gemm_loop(LAS unsigned char* lds, const bf16_t* __restrict__ A, int lda, const bf16_t* __restrict__ B, int ldb, int K, const Epi& epi, int t0, int tstep, int tend, const TileFn& tf) {
;     ...
;             LDA(At, 1, 1); STG_B(1, 0, b3); STG_B(1, 1, b3); STG_A(1, 0, a3);
;             WAIT_V(8); WAIT_L(0); BAR; MMA(1, 0, At, B0); MMA(1, 1, At, B1); BAR; SCHED;
;         }
;         if (wr == 0) BAR;
	s_add_u32 s28, s8, 0x400000
	s_addc_u32 s29, s9, 0
	v_readfirstlane_b32 s7, v147
	v_lshl_add_u64 v[238:239], s[28:29], 0, v[194:195]
	s_mov_b32 m0, s7
	v_readfirstlane_b32 s7, v148
	s_add_u32 s8, s8, 0x400800
	ds_read_b128 v[196:199], v154 offset:49152
	ds_read_b128 v[200:203], v154 offset:50176
	ds_read_b128 v[212:215], v154 offset:51200
	ds_read_b128 v[216:219], v154 offset:52224
	ds_read_b128 v[220:223], v154 offset:53248
	ds_read_b128 v[224:227], v154 offset:54272
	ds_read_b128 v[228:231], v154 offset:55296
	ds_read_b128 v[232:235], v154 offset:56320
	global_load_lds_dwordx4 v[238:239], off
	v_lshl_add_u64 v[238:239], s[28:29], 0, v[132:133]
	s_mov_b32 m0, s7
	s_addc_u32 s9, s9, 0
	v_readfirstlane_b32 s7, v151
	global_load_lds_dwordx4 v[238:239], off
	v_lshl_add_u64 v[238:239], s[8:9], 0, v[194:195]
	s_mov_b32 m0, s7
	v_readfirstlane_b32 s7, v152
	global_load_lds_dwordx4 v[238:239], off
	v_lshl_add_u64 v[238:239], s[8:9], 0, v[132:133]
	s_mov_b32 m0, s7
	v_readfirstlane_b32 s7, v149
	global_load_lds_dwordx4 v[238:239], off
	v_lshl_add_u64 v[204:205], v[204:205], 0, s[2:3]
	s_mov_b32 m0, s7
	v_readfirstlane_b32 s7, v150
	global_load_lds_dwordx4 v[204:205], off
	v_lshl_add_u64 v[204:205], v[236:237], 0, s[2:3]
	s_mov_b32 m0, s7
	s_nop 0
	global_load_lds_dwordx4 v[204:205], off
	s_waitcnt vmcnt(8)
	s_waitcnt lgkmcnt(0)
	s_barrier
	s_waitcnt lgkmcnt(0)
	v_mfma_f32_16x16x32_bf16 v[60:63], v[156:159], v[196:199], v[60:63]
	v_mfma_f32_16x16x32_bf16 v[56:59], v[164:167], v[196:199], v[56:59]
	v_mfma_f32_16x16x32_bf16 v[44:47], v[156:159], v[212:215], v[44:47]
	v_mfma_f32_16x16x32_bf16 v[40:43], v[164:167], v[212:215], v[40:43]
	v_mfma_f32_16x16x32_bf16 v[28:31], v[156:159], v[220:223], v[28:31]
	v_mfma_f32_16x16x32_bf16 v[24:27], v[164:167], v[220:223], v[24:27]
	v_mfma_f32_16x16x32_bf16 v[12:15], v[156:159], v[228:231], v[12:15]
	v_mfma_f32_16x16x32_bf16 v[8:11], v[164:167], v[228:231], v[8:11]
	v_mfma_f32_16x16x32_bf16 v[60:63], v[160:163], v[200:203], v[60:63]
	v_mfma_f32_16x16x32_bf16 v[56:59], v[168:171], v[200:203], v[56:59]
	v_mfma_f32_16x16x32_bf16 v[44:47], v[160:163], v[216:219], v[44:47]
	v_mfma_f32_16x16x32_bf16 v[40:43], v[168:171], v[216:219], v[40:43]
	v_mfma_f32_16x16x32_bf16 v[28:31], v[160:163], v[224:227], v[28:31]
	v_mfma_f32_16x16x32_bf16 v[24:27], v[168:171], v[224:227], v[24:27]
	v_mfma_f32_16x16x32_bf16 v[12:15], v[160:163], v[232:235], v[12:15]
	v_mfma_f32_16x16x32_bf16 v[8:11], v[168:171], v[232:235], v[8:11]
	v_mfma_f32_16x16x32_bf16 v[52:55], v[172:175], v[196:199], v[52:55]
	v_mfma_f32_16x16x32_bf16 v[48:51], v[180:183], v[196:199], v[48:51]
	v_mfma_f32_16x16x32_bf16 v[36:39], v[172:175], v[212:215], v[36:39]
	v_mfma_f32_16x16x32_bf16 v[32:35], v[180:183], v[212:215], v[32:35]
	v_mfma_f32_16x16x32_bf16 v[20:23], v[172:175], v[220:223], v[20:23]
	v_mfma_f32_16x16x32_bf16 v[16:19], v[180:183], v[220:223], v[16:19]
	v_mfma_f32_16x16x32_bf16 v[4:7], v[172:175], v[228:231], v[4:7]
	v_mfma_f32_16x16x32_bf16 v[0:3], v[180:183], v[228:231], v[0:3]
	v_mfma_f32_16x16x32_bf16 v[52:55], v[176:179], v[200:203], v[52:55]
	v_mfma_f32_16x16x32_bf16 v[48:51], v[184:187], v[200:203], v[48:51]
	v_mfma_f32_16x16x32_bf16 v[36:39], v[176:179], v[216:219], v[36:39]
	v_mfma_f32_16x16x32_bf16 v[32:35], v[184:187], v[216:219], v[32:35]
	v_mfma_f32_16x16x32_bf16 v[20:23], v[176:179], v[224:227], v[20:23]
	v_mfma_f32_16x16x32_bf16 v[16:19], v[184:187], v[224:227], v[16:19]
	v_mfma_f32_16x16x32_bf16 v[4:7], v[176:179], v[232:235], v[4:7]
	v_mfma_f32_16x16x32_bf16 v[0:3], v[184:187], v[232:235], v[0:3]
	s_barrier
	s_add_i32 s4, s4, 2
	s_add_u32 s0, s0, 0x800000
	s_addc_u32 s1, s1, 0
	s_add_u32 s36, s36, 0x100
	s_addc_u32 s37, s37, 0
	s_cmp_gt_u32 s4, 7
	s_cbranch_scc0 .LBB0_648
	s_setprio 0
	s_movk_i32 s0, 0x100
	v_cmp_gt_u32_e32 vcc, s0, v138
	s_and_saveexec_b64 s[0:1], vcc
	s_cbranch_execz .LBB0_651
	s_barrier

; #define LAS __attribute__((address_space(3)))
; #define WAIT_V(n) asm volatile("s_waitcnt vmcnt(" #n ")" ::: "memory")
; #define WAIT_L(n) asm volatile("s_waitcnt lgkmcnt(" #n ")" ::: "memory")
; #define BAR __builtin_amdgcn_s_barrier()
; #define SCHED __builtin_amdgcn_sched_barrier(0)
; #define STG_A(b, h, ptr) do { const char* _g = (ptr) + (h) * ahalf; LAS unsigned char* _l = lw + ((b) * 2 + (h)) * 16384; GLDS(_g + voa0, _l); GLDS(_g + voa1, _l + 8192); } while (0)
; #define STG_B(b, h, ptr) do { const char* _g = (ptr) + (h) * bhalf; LAS unsigned char* _l = lw + 65536 + ((b) * 2 + (h)) * 16384; GLDS(_g + vob0, _l); GLDS(_g + vob1, _l + 8192); } while (0)
; template <int BMODE, class Epi, class TileFn>
; DEV void gemm_loop(LAS unsigned char* lds, const bf16_t* __restrict__ A, int lda, const bf16_t* __restrict__ B, int ldb, int K, const Epi& epi, int t0, int tstep, int tend, const TileFn& tf) {
;     ...
;     if (BMODE == 0) { vob0 = (unsigned)(r0b * ldb + c0) * 2u; vob1 = vob0 + (unsigned)(64 * ldb) * 2u; bks = 128; bhalf = (size_t)128 * ldb * 2; }
;     else { vob0 = (unsigned)((c0 >> 3) * ldb + r0b) * 16u; vob1 = vob0 + 64u * 16u; bks = (size_t)ldb * 128; bhalf = 128 * 16; }
;     LAS unsigned char* lw = lds + tid * 16;
;     const int sw = swz_off(fr, fq);
;     LAS unsigned char* la = lds + wr * 8192 + sw;
;     LAS unsigned char* lb = lds + 65536 + wc * 4096 + sw;
;     int brow, bcol; tf(t0, brow, bcol);
;     const char* cA = (const char*)(A + (size_t)brow * lda);
;     const char* cB = BMODE == 0 ? (const char*)(B + (size_t)bcol * ldb) : (const char*)(B + (size_t)bcol * 8);
;     ...
;     const int nt = K / 64;
;     f32x4 acc[2][2][4][2];
; #pragma unroll
;     for (int a = 0; a < 2; ++a)
; #pragma unroll
;         for (int b = 0; b < 2; ++b)
; #pragma unroll
;             for (int m = 0; m < 4; ++m)
; #pragma unroll
;                 for (int n = 0; n < 2; ++n) acc[a][b][m][n] = (f32x4){0.f, 0.f, 0.f, 0.f};
;     bf16x8 At[4][2], B0[2][2], B1[2][2];
;     STG_B(0, 0, cB); STG_B(0, 1, cB); STG_A(0, 0, cA); STG_A(0, 1, cA);
;     if (wr == 1) BAR;
;     WAIT_V(2); BAR;
;     STG_B(1, 0, cB + bks); STG_A(1, 0, cA + 128); STG_B(1, 1, cB + bks);
;     WAIT_V(6); BAR;
;     ...
;             LDB(B0, 0, 0); LDB(B1, 0, 1); SCHED; LDA(At, 0, 0); STG_A(1, 1, a1);
;             WAIT_V(8); WAIT_L(0); BAR; MMA(0, 0, At, B0); MMA(0, 1, At, B1); BAR; SCHED;
.LBB0_687:
	s_or_b64 exec, exec, s[0:1]
	v_lshl_add_u32 v11, v4, 13, 0
	v_lshlrev_b32_e32 v4, 6, v138
	v_and_b32_e32 v5, 15, v138
	v_lshlrev_b32_e32 v10, 2, v138
	v_and_b32_e32 v4, 0x3000, v4
	s_add_i32 s0, 0, 0x10000
	v_add_u32_e32 v147, 0x18000, v139
	v_readlane_b32 s8, v253, 42
	v_readlane_b32 s40, v253, 38
	v_lshlrev_b32_e32 v5, 6, v5
	v_and_b32_e32 v10, 32, v10
	v_add_u32_e32 v12, s0, v4
	v_and_b32_e32 v4, 48, v138
	v_readlane_b32 s9, v253, 43
	v_readfirstlane_b32 s0, v147
	v_add_u32_e32 v148, 0x1a000, v139
	v_mov_b32_e32 v129, v195
	v_readlane_b32 s41, v253, 39
	v_bitop3_b32 v10, v5, v10, v4 bitop3:0x36
	v_lshl_add_u64 v[4:5], s[8:9], 0, v[194:195]
	s_mov_b32 m0, s0
	v_readfirstlane_b32 s0, v148
	v_add_u32_e32 v149, 0x8000, v139
	v_lshl_add_u64 v[6:7], s[40:41], 0, v[128:129]
	v_mov_b32_e32 v131, v195
	s_waitcnt vmcnt(2)
	s_barrier
	global_load_lds_dwordx4 v[4:5], off
	v_lshl_add_u64 v[4:5], s[8:9], 0, v[132:133]
	s_mov_b32 m0, s0
	v_readfirstlane_b32 s0, v149
	v_add_u32_e32 v150, 0xa000, v139
	v_lshl_add_u64 v[8:9], s[40:41], 0, v[130:131]
	global_load_lds_dwordx4 v[4:5], off
	v_lshl_add_u64 v[4:5], v[6:7], 0, s[2:3]
	s_mov_b32 m0, s0
	v_readfirstlane_b32 s0, v150
	v_add_u32_e32 v151, 0x1c000, v139
	v_readlane_b32 s8, v253, 46
	global_load_lds_dwordx4 v[4:5], off
	v_lshl_add_u64 v[4:5], v[8:9], 0, s[2:3]
	s_mov_b32 m0, s0
	v_readlane_b32 s9, v253, 47
	v_readfirstlane_b32 s0, v151
	v_add_u32_e32 v152, 0x1e000, v139
	global_load_lds_dwordx4 v[4:5], off
	v_lshl_add_u64 v[4:5], s[8:9], 0, v[194:195]
	s_mov_b32 m0, s0
	v_readfirstlane_b32 s0, v152
	global_load_lds_dwordx4 v[4:5], off
	v_lshl_add_u64 v[4:5], s[8:9], 0, v[132:133]
	s_mov_b32 m0, s0
	v_lshrrev_b32_e32 v2, 4, v2
	global_load_lds_dwordx4 v[4:5], off
	s_mov_b32 s0, 0x8800
	v_mul_lo_u32 v2, v2, s0
	v_or_b32_e32 v2, v3, v2
	s_movk_i32 s0, 0x880
	v_mad_u32_u24 v0, v0, s0, v2
	v_readlane_b32 s0, v254, 57
	v_add_lshl_u32 v0, v0, v1, 1
	v_mov_b32_e32 v1, v195
	v_readlane_b32 s1, v254, 58
	s_waitcnt vmcnt(6)
	v_readlane_b32 s30, v253, 44
	s_mov_b32 s4, -2
	v_lshl_add_u64 v[134:135], s[0:1], 0, v[0:1]
	v_add_u32_e32 v0, 0x44000, v0
	v_lshl_add_u64 v[136:137], s[0:1], 0, v[0:1]
	s_mov_b64 s[0:1], 0x100000
	s_mov_b64 s[36:37], 0x5ad0080
	v_add_u32_e32 v153, v12, v10
	v_add_u32_e32 v154, v11, v10
	v_readlane_b32 s31, v253, 45
	s_barrier
	v_readfirstlane_b32 s100, v188
	s_nop 3
	s_cmp_lt_u32 s100, 0x100
	s_cbranch_scc1 .Lsp_688
	s_setprio 1
.Lsp_688:
	ds_read_b128 v[156:159], v153
	ds_read_b128 v[160:163], v153 offset:1024
	ds_read_b128 v[164:167], v153 offset:2048
	ds_read_b128 v[168:171], v153 offset:3072
	ds_read_b128 v[172:175], v153 offset:16384
	ds_read_b128 v[176:179], v153 offset:17408
	ds_read_b128 v[180:183], v153 offset:18432
	ds_read_b128 v[184:187], v153 offset:19456
	s_add_u32 s7, s36, 0xfa530080
	s_addc_u32 s8, s37, -1
	s_cmp_eq_u32 s4, 30
	s_cselect_b32 s7, 0, s7
	s_cselect_b32 s8, 0, s8
	s_cselect_b32 s9, 0, s0
	s_cselect_b32 s28, 0, s1
	s_add_u32 s38, s40, s7
	s_addc_u32 s39, s41, s8
	s_add_u32 s8, s30, s9
	s_addc_u32 s9, s31, s28
	v_add_u32_e32 v155, 0xc000, v139
	v_lshl_add_u64 v[204:205], v[134:135], 0, s[36:37]
	v_readfirstlane_b32 s7, v155
	v_add_u32_e32 v155, 0xe000, v139
	s_mov_b32 m0, s7
	v_readfirstlane_b32 s7, v155
	ds_read_b128 v[196:199], v154
	ds_read_b128 v[200:203], v154 offset:1024
	ds_read_b128 v[212:215], v154 offset:2048
	ds_read_b128 v[216:219], v154 offset:3072
	ds_read_b128 v[220:223], v154 offset:4096
	ds_read_b128 v[224:227], v154 offset:5120
	ds_read_b128 v[228:231], v154 offset:6144
	ds_read_b128 v[232:235], v154 offset:7168
	global_load_lds_dwordx4 v[204:205], off
	v_lshl_add_u64 v[204:205], v[136:137], 0, s[36:37]
	s_mov_b32 m0, s7
	s_nop 0
	global_load_lds_dwordx4 v[204:205], off
	s_waitcnt vmcnt(8)
	s_waitcnt lgkmcnt(0)
	s_barrier
	s_waitcnt lgkmcnt(0)
	v_mfma_f32_16x16x32_bf16 v[124:127], v[156:159], v[196:199], 0
	v_mfma_f32_16x16x32_bf16 v[120:123], v[164:167], v[196:199], 0
	v_mfma_f32_16x16x32_bf16 v[108:111], v[156:159], v[212:215], 0
	v_mfma_f32_16x16x32_bf16 v[104:107], v[164:167], v[212:215], 0
	v_mfma_f32_16x16x32_bf16 v[92:95], v[156:159], v[220:223], 0
	v_mfma_f32_16x16x32_bf16 v[88:91], v[164:167], v[220:223], 0
	v_mfma_f32_16x16x32_bf16 v[76:79], v[156:159], v[228:231], 0
	v_mfma_f32_16x16x32_bf16 v[72:75], v[164:167], v[228:231], 0
	v_mfma_f32_16x16x32_bf16 v[124:127], v[160:163], v[200:203], v[124:127]
	v_mfma_f32_16x16x32_bf16 v[120:123], v[168:171], v[200:203], v[120:123]
	v_mfma_f32_16x16x32_bf16 v[108:111], v[160:163], v[216:219], v[108:111]
	v_mfma_f32_16x16x32_bf16 v[104:107], v[168:171], v[216:219], v[104:107]
	v_mfma_f32_16x16x32_bf16 v[92:95], v[160:163], v[224:227], v[92:95]
	v_mfma_f32_16x16x32_bf16 v[88:91], v[168:171], v[224:227], v[88:91]
	v_mfma_f32_16x16x32_bf16 v[76:79], v[160:163], v[232:235], v[76:79]
	v_mfma_f32_16x16x32_bf16 v[72:75], v[168:171], v[232:235], v[72:75]
	v_mfma_f32_16x16x32_bf16 v[116:119], v[172:175], v[196:199], 0
	v_mfma_f32_16x16x32_bf16 v[112:115], v[180:183], v[196:199], 0
	v_mfma_f32_16x16x32_bf16 v[100:103], v[172:175], v[212:215], 0
	v_mfma_f32_16x16x32_bf16 v[96:99], v[180:183], v[212:215], 0
	v_mfma_f32_16x16x32_bf16 v[84:87], v[172:175], v[220:223], 0
	v_mfma_f32_16x16x32_bf16 v[80:83], v[180:183], v[220:223], 0
	v_mfma_f32_16x16x32_bf16 v[68:71], v[172:175], v[228:231], 0
	v_mfma_f32_16x16x32_bf16 v[64:67], v[180:183], v[228:231], 0
	v_mfma_f32_16x16x32_bf16 v[116:119], v[176:179], v[200:203], v[116:119]
	v_mfma_f32_16x16x32_bf16 v[112:115], v[184:187], v[200:203], v[112:115]
	v_mfma_f32_16x16x32_bf16 v[100:103], v[176:179], v[216:219], v[100:103]
	v_mfma_f32_16x16x32_bf16 v[96:99], v[184:187], v[216:219], v[96:99]
	v_mfma_f32_16x16x32_bf16 v[84:87], v[176:179], v[224:227], v[84:87]
	v_mfma_f32_16x16x32_bf16 v[80:83], v[184:187], v[224:227], v[80:83]
	v_mfma_f32_16x16x32_bf16 v[68:71], v[176:179], v[232:235], v[68:71]
	v_mfma_f32_16x16x32_bf16 v[64:67], v[184:187], v[232:235], v[64:67]
	s_barrier
; #define WAIT_V(n) asm volatile("s_waitcnt vmcnt(" #n ")" ::: "memory")
; #define WAIT_L(n) asm volatile("s_waitcnt lgkmcnt(" #n ")" ::: "memory")
; #define BAR __builtin_amdgcn_s_barrier()
; #define SCHED __builtin_amdgcn_sched_barrier(0)
; #define STG_A(b, h, ptr) do { const char* _g = (ptr) + (h) * ahalf; LAS unsigned char* _l = lw + ((b) * 2 + (h)) * 16384; GLDS(_g + voa0, _l); GLDS(_g + voa1, _l + 8192); } while (0)
; #define STG_B(b, h, ptr) do { const char* _g = (ptr) + (h) * bhalf; LAS unsigned char* _l = lw + 65536 + ((b) * 2 + (h)) * 16384; GLDS(_g + vob0, _l); GLDS(_g + vob1, _l + 8192); } while (0)
; #define LDA(dst, b, h) _Pragma("unroll") for (int m = 0; m < 4; ++m) _Pragma("unroll") for (int k = 0; k < 2; ++k) dst[m][k] = *(const LAS bf16x8*)(la + ((b) * 2 + (h)) * 16384 + m * 2048 + k * 1024)
; #define LDB(dst, b, h) _Pragma("unroll") for (int n = 0; n < 2; ++n) _Pragma("unroll") for (int k = 0; k < 2; ++k) dst[n][k] = *(const LAS bf16x8*)(lb + ((b) * 2 + (h)) * 16384 + n * 2048 + k * 1024)
; #define MMA(ai, bj, Af, Bf) do { __builtin_amdgcn_s_setprio(1); \
;     _Pragma("unroll") for (int m = 0; m < 4; ++m) _Pragma("unroll") for (int n = 0; n < 2; ++n) _Pragma("unroll") for (int k = 0; k < 2; ++k) \
;         acc[ai][bj][m][n] = __builtin_amdgcn_mfma_f32_16x16x32_bf16(Bf[n][k], Af[m][k], acc[ai][bj][m][n], 0, 0, 0); \
;     __builtin_amdgcn_s_setprio(0); } while (0)
; template <int BMODE, class Epi, class TileFn>
; DEV void gemm_loop(LAS unsigned char* lds, const bf16_t* __restrict__ A, int lda, const bf16_t* __restrict__ B, int ldb, int K, const Epi& epi, int t0, int tstep, int tend, const TileFn& tf) {
;     ...
;             LDB(B0, 0, 0); LDB(B1, 0, 1); SCHED; LDA(At, 0, 0); STG_A(1, 1, a1);
;             WAIT_V(8); WAIT_L(0); BAR; MMA(0, 0, At, B0); MMA(0, 1, At, B1); BAR; SCHED;
;             LDA(At, 0, 1); STG_B(0, 0, b2); STG_B(0, 1, b2); STG_A(0, 0, a2);
;             WAIT_V(8); WAIT_L(0); BAR; MMA(1, 0, At, B0); MMA(1, 1, At, B1); BAR; SCHED;
	v_readfirstlane_b32 s7, v140
	v_lshl_add_u64 v[204:205], s[8:9], 0, v[194:195]
	s_mov_b32 m0, s7
	v_readfirstlane_b32 s7, v141
	ds_read_b128 v[196:199], v154 offset:16384
	ds_read_b128 v[200:203], v154 offset:17408
	ds_read_b128 v[212:215], v154 offset:18432
	ds_read_b128 v[216:219], v154 offset:19456
	ds_read_b128 v[220:223], v154 offset:20480
	ds_read_b128 v[224:227], v154 offset:21504
	ds_read_b128 v[228:231], v154 offset:22528
	ds_read_b128 v[232:235], v154 offset:23552
	global_load_lds_dwordx4 v[204:205], off
	v_lshl_add_u64 v[236:237], s[8:9], 0, v[132:133]
	s_mov_b32 m0, s7
	v_readfirstlane_b32 s7, v142
	global_load_lds_dwordx4 v[236:237], off
	v_lshl_add_u64 v[204:205], v[204:205], 0, s[86:87]
	s_mov_b32 m0, s7
	v_readfirstlane_b32 s7, v143
	global_load_lds_dwordx4 v[204:205], off
	v_lshl_add_u64 v[204:205], v[236:237], 0, s[86:87]
	s_mov_b32 m0, s7
	v_readfirstlane_b32 s7, v139
	global_load_lds_dwordx4 v[204:205], off
	v_lshl_add_u64 v[204:205], s[38:39], 0, v[128:129]
	s_mov_b32 m0, s7
	v_readfirstlane_b32 s7, v144
	global_load_lds_dwordx4 v[204:205], off
	v_lshl_add_u64 v[236:237], s[38:39], 0, v[130:131]
	s_mov_b32 m0, s7
	s_nop 0
	global_load_lds_dwordx4 v[236:237], off
	s_waitcnt vmcnt(8)
	s_waitcnt lgkmcnt(0)
	s_barrier
	s_waitcnt lgkmcnt(0)
	v_mfma_f32_16x16x32_bf16 v[60:63], v[156:159], v[196:199], 0
	v_mfma_f32_16x16x32_bf16 v[56:59], v[164:167], v[196:199], 0
	v_mfma_f32_16x16x32_bf16 v[44:47], v[156:159], v[212:215], 0
	v_mfma_f32_16x16x32_bf16 v[40:43], v[164:167], v[212:215], 0
	v_mfma_f32_16x16x32_bf16 v[28:31], v[156:159], v[220:223], 0
	v_mfma_f32_16x16x32_bf16 v[24:27], v[164:167], v[220:223], 0
	v_mfma_f32_16x16x32_bf16 v[12:15], v[156:159], v[228:231], 0
	v_mfma_f32_16x16x32_bf16 v[8:11], v[164:167], v[228:231], 0
	v_mfma_f32_16x16x32_bf16 v[60:63], v[160:163], v[200:203], v[60:63]
	v_mfma_f32_16x16x32_bf16 v[56:59], v[168:171], v[200:203], v[56:59]
	v_mfma_f32_16x16x32_bf16 v[44:47], v[160:163], v[216:219], v[44:47]
	v_mfma_f32_16x16x32_bf16 v[40:43], v[168:171], v[216:219], v[40:43]
	v_mfma_f32_16x16x32_bf16 v[28:31], v[160:163], v[224:227], v[28:31]
	v_mfma_f32_16x16x32_bf16 v[24:27], v[168:171], v[224:227], v[24:27]
	v_mfma_f32_16x16x32_bf16 v[12:15], v[160:163], v[232:235], v[12:15]
	v_mfma_f32_16x16x32_bf16 v[8:11], v[168:171], v[232:235], v[8:11]
	v_mfma_f32_16x16x32_bf16 v[52:55], v[172:175], v[196:199], 0
	v_mfma_f32_16x16x32_bf16 v[48:51], v[180:183], v[196:199], 0
	v_mfma_f32_16x16x32_bf16 v[36:39], v[172:175], v[212:215], 0
	v_mfma_f32_16x16x32_bf16 v[32:35], v[180:183], v[212:215], 0
	v_mfma_f32_16x16x32_bf16 v[20:23], v[172:175], v[220:223], 0
	v_mfma_f32_16x16x32_bf16 v[16:19], v[180:183], v[220:223], 0
	v_mfma_f32_16x16x32_bf16 v[4:7], v[172:175], v[228:231], 0
	v_mfma_f32_16x16x32_bf16 v[0:3], v[180:183], v[228:231], 0
	v_mfma_f32_16x16x32_bf16 v[52:55], v[176:179], v[200:203], v[52:55]
	v_mfma_f32_16x16x32_bf16 v[48:51], v[184:187], v[200:203], v[48:51]
	v_mfma_f32_16x16x32_bf16 v[36:39], v[176:179], v[216:219], v[36:39]
	v_mfma_f32_16x16x32_bf16 v[32:35], v[184:187], v[216:219], v[32:35]
	v_mfma_f32_16x16x32_bf16 v[20:23], v[176:179], v[224:227], v[20:23]
	v_mfma_f32_16x16x32_bf16 v[16:19], v[184:187], v[224:227], v[16:19]
	v_mfma_f32_16x16x32_bf16 v[4:7], v[176:179], v[232:235], v[4:7]
	v_mfma_f32_16x16x32_bf16 v[0:3], v[184:187], v[232:235], v[0:3]
	s_barrier
	s_branch .Lkmid_688
.LBB0_688:
	ds_read_b128 v[156:159], v153
	ds_read_b128 v[160:163], v153 offset:1024
	ds_read_b128 v[164:167], v153 offset:2048
	ds_read_b128 v[168:171], v153 offset:3072
	ds_read_b128 v[172:175], v153 offset:16384
	ds_read_b128 v[176:179], v153 offset:17408
	ds_read_b128 v[180:183], v153 offset:18432
	ds_read_b128 v[184:187], v153 offset:19456
	s_add_u32 s7, s36, 0xfa530080
	s_addc_u32 s8, s37, -1
	s_cmp_eq_u32 s4, 30
	s_cselect_b32 s7, 0, s7
	s_cselect_b32 s8, 0, s8
	s_cselect_b32 s9, 0, s0
	s_cselect_b32 s28, 0, s1
	s_add_u32 s38, s40, s7
	s_addc_u32 s39, s41, s8
	s_add_u32 s8, s30, s9
	s_addc_u32 s9, s31, s28
	v_add_u32_e32 v155, 0xc000, v139
	v_lshl_add_u64 v[204:205], v[134:135], 0, s[36:37]
	v_readfirstlane_b32 s7, v155
	v_add_u32_e32 v155, 0xe000, v139
	s_mov_b32 m0, s7
	v_readfirstlane_b32 s7, v155
	ds_read_b128 v[196:199], v154
	ds_read_b128 v[200:203], v154 offset:1024
	ds_read_b128 v[212:215], v154 offset:2048
	ds_read_b128 v[216:219], v154 offset:3072
	ds_read_b128 v[220:223], v154 offset:4096
	ds_read_b128 v[224:227], v154 offset:5120
	ds_read_b128 v[228:231], v154 offset:6144
	ds_read_b128 v[232:235], v154 offset:7168
	global_load_lds_dwordx4 v[204:205], off
	v_lshl_add_u64 v[204:205], v[136:137], 0, s[36:37]
	s_mov_b32 m0, s7
	s_nop 0
	global_load_lds_dwordx4 v[204:205], off
	s_waitcnt vmcnt(8)
	s_waitcnt lgkmcnt(0)
	s_barrier
; #define WAIT_V(n) asm volatile("s_waitcnt vmcnt(" #n ")" ::: "memory")
; #define WAIT_L(n) asm volatile("s_waitcnt lgkmcnt(" #n ")" ::: "memory")
; #define BAR __builtin_amdgcn_s_barrier()
; #define SCHED __builtin_amdgcn_sched_barrier(0)
; #define STG_A(b, h, ptr) do { const char* _g = (ptr) + (h) * ahalf; LAS unsigned char* _l = lw + ((b) * 2 + (h)) * 16384; GLDS(_g + voa0, _l); GLDS(_g + voa1, _l + 8192); } while (0)
; #define STG_B(b, h, ptr) do { const char* _g = (ptr) + (h) * bhalf; LAS unsigned char* _l = lw + 65536 + ((b) * 2 + (h)) * 16384; GLDS(_g + vob0, _l); GLDS(_g + vob1, _l + 8192); } while (0)
; #define LDA(dst, b, h) _Pragma("unroll") for (int m = 0; m < 4; ++m) _Pragma("unroll") for (int k = 0; k < 2; ++k) dst[m][k] = *(const LAS bf16x8*)(la + ((b) * 2 + (h)) * 16384 + m * 2048 + k * 1024)
; #define MMA(ai, bj, Af, Bf) do { __builtin_amdgcn_s_setprio(1); \
;     _Pragma("unroll") for (int m = 0; m < 4; ++m) _Pragma("unroll") for (int n = 0; n < 2; ++n) _Pragma("unroll") for (int k = 0; k < 2; ++k) \
;         acc[ai][bj][m][n] = __builtin_amdgcn_mfma_f32_16x16x32_bf16(Bf[n][k], Af[m][k], acc[ai][bj][m][n], 0, 0, 0); \
;     __builtin_amdgcn_s_setprio(0); } while (0)
; template <int BMODE, class Epi, class TileFn>
; DEV void gemm_loop(LAS unsigned char* lds, const bf16_t* __restrict__ A, int lda, const bf16_t* __restrict__ B, int ldb, int K, const Epi& epi, int t0, int tstep, int tend, const TileFn& tf) {
;     ...
;             WAIT_V(8); WAIT_L(0); BAR; MMA(0, 0, At, B0); MMA(0, 1, At, B1); BAR; SCHED;
;             LDA(At, 0, 1); STG_B(0, 0, b2); STG_B(0, 1, b2); STG_A(0, 0, a2);
;             WAIT_V(8); WAIT_L(0); BAR; MMA(1, 0, At, B0); MMA(1, 1, At, B1); BAR; SCHED;
	s_waitcnt lgkmcnt(0)
	v_mfma_f32_16x16x32_bf16 v[124:127], v[156:159], v[196:199], v[124:127]
	v_mfma_f32_16x16x32_bf16 v[120:123], v[164:167], v[196:199], v[120:123]
	v_mfma_f32_16x16x32_bf16 v[108:111], v[156:159], v[212:215], v[108:111]
	v_mfma_f32_16x16x32_bf16 v[104:107], v[164:167], v[212:215], v[104:107]
	v_mfma_f32_16x16x32_bf16 v[92:95], v[156:159], v[220:223], v[92:95]
	v_mfma_f32_16x16x32_bf16 v[88:91], v[164:167], v[220:223], v[88:91]
	v_mfma_f32_16x16x32_bf16 v[76:79], v[156:159], v[228:231], v[76:79]
	v_mfma_f32_16x16x32_bf16 v[72:75], v[164:167], v[228:231], v[72:75]
	v_mfma_f32_16x16x32_bf16 v[124:127], v[160:163], v[200:203], v[124:127]
	v_mfma_f32_16x16x32_bf16 v[120:123], v[168:171], v[200:203], v[120:123]
	v_mfma_f32_16x16x32_bf16 v[108:111], v[160:163], v[216:219], v[108:111]
	v_mfma_f32_16x16x32_bf16 v[104:107], v[168:171], v[216:219], v[104:107]
	v_mfma_f32_16x16x32_bf16 v[92:95], v[160:163], v[224:227], v[92:95]
	v_mfma_f32_16x16x32_bf16 v[88:91], v[168:171], v[224:227], v[88:91]
	v_mfma_f32_16x16x32_bf16 v[76:79], v[160:163], v[232:235], v[76:79]
	v_mfma_f32_16x16x32_bf16 v[72:75], v[168:171], v[232:235], v[72:75]
	v_mfma_f32_16x16x32_bf16 v[116:119], v[172:175], v[196:199], v[116:119]
	v_mfma_f32_16x16x32_bf16 v[112:115], v[180:183], v[196:199], v[112:115]
	v_mfma_f32_16x16x32_bf16 v[100:103], v[172:175], v[212:215], v[100:103]
	v_mfma_f32_16x16x32_bf16 v[96:99], v[180:183], v[212:215], v[96:99]
	v_mfma_f32_16x16x32_bf16 v[84:87], v[172:175], v[220:223], v[84:87]
	v_mfma_f32_16x16x32_bf16 v[80:83], v[180:183], v[220:223], v[80:83]
	v_mfma_f32_16x16x32_bf16 v[68:71], v[172:175], v[228:231], v[68:71]
	v_mfma_f32_16x16x32_bf16 v[64:67], v[180:183], v[228:231], v[64:67]
	v_mfma_f32_16x16x32_bf16 v[116:119], v[176:179], v[200:203], v[116:119]
	v_mfma_f32_16x16x32_bf16 v[112:115], v[184:187], v[200:203], v[112:115]
	v_mfma_f32_16x16x32_bf16 v[100:103], v[176:179], v[216:219], v[100:103]
	v_mfma_f32_16x16x32_bf16 v[96:99], v[184:187], v[216:219], v[96:99]
	v_mfma_f32_16x16x32_bf16 v[84:87], v[176:179], v[224:227], v[84:87]
	v_mfma_f32_16x16x32_bf16 v[80:83], v[184:187], v[224:227], v[80:83]
	v_mfma_f32_16x16x32_bf16 v[68:71], v[176:179], v[232:235], v[68:71]
	v_mfma_f32_16x16x32_bf16 v[64:67], v[184:187], v[232:235], v[64:67]
	s_barrier
	v_readfirstlane_b32 s7, v140
	v_lshl_add_u64 v[204:205], s[8:9], 0, v[194:195]
	s_mov_b32 m0, s7
	v_readfirstlane_b32 s7, v141
	ds_read_b128 v[196:199], v154 offset:16384
	ds_read_b128 v[200:203], v154 offset:17408
	ds_read_b128 v[212:215], v154 offset:18432
	ds_read_b128 v[216:219], v154 offset:19456
	ds_read_b128 v[220:223], v154 offset:20480
	ds_read_b128 v[224:227], v154 offset:21504
	ds_read_b128 v[228:231], v154 offset:22528
	ds_read_b128 v[232:235], v154 offset:23552
	global_load_lds_dwordx4 v[204:205], off
	v_lshl_add_u64 v[236:237], s[8:9], 0, v[132:133]
	s_mov_b32 m0, s7
	v_readfirstlane_b32 s7, v142
	global_load_lds_dwordx4 v[236:237], off
	v_lshl_add_u64 v[204:205], v[204:205], 0, s[86:87]
	s_mov_b32 m0, s7
	v_readfirstlane_b32 s7, v143
	global_load_lds_dwordx4 v[204:205], off
	v_lshl_add_u64 v[204:205], v[236:237], 0, s[86:87]
	s_mov_b32 m0, s7
	v_readfirstlane_b32 s7, v139
	global_load_lds_dwordx4 v[204:205], off
	v_lshl_add_u64 v[204:205], s[38:39], 0, v[128:129]
	s_mov_b32 m0, s7
	v_readfirstlane_b32 s7, v144
	global_load_lds_dwordx4 v[204:205], off
	v_lshl_add_u64 v[236:237], s[38:39], 0, v[130:131]
	s_mov_b32 m0, s7
	s_nop 0
	global_load_lds_dwordx4 v[236:237], off
	s_waitcnt vmcnt(8)
	s_waitcnt lgkmcnt(0)
	s_barrier
	s_waitcnt lgkmcnt(0)
	v_mfma_f32_16x16x32_bf16 v[60:63], v[156:159], v[196:199], v[60:63]
	v_mfma_f32_16x16x32_bf16 v[56:59], v[164:167], v[196:199], v[56:59]
	v_mfma_f32_16x16x32_bf16 v[44:47], v[156:159], v[212:215], v[44:47]
	v_mfma_f32_16x16x32_bf16 v[40:43], v[164:167], v[212:215], v[40:43]
	v_mfma_f32_16x16x32_bf16 v[28:31], v[156:159], v[220:223], v[28:31]
	v_mfma_f32_16x16x32_bf16 v[24:27], v[164:167], v[220:223], v[24:27]
	v_mfma_f32_16x16x32_bf16 v[12:15], v[156:159], v[228:231], v[12:15]
	v_mfma_f32_16x16x32_bf16 v[8:11], v[164:167], v[228:231], v[8:11]
	v_mfma_f32_16x16x32_bf16 v[60:63], v[160:163], v[200:203], v[60:63]
	v_mfma_f32_16x16x32_bf16 v[56:59], v[168:171], v[200:203], v[56:59]
	v_mfma_f32_16x16x32_bf16 v[44:47], v[160:163], v[216:219], v[44:47]
	v_mfma_f32_16x16x32_bf16 v[40:43], v[168:171], v[216:219], v[40:43]
	v_mfma_f32_16x16x32_bf16 v[28:31], v[160:163], v[224:227], v[28:31]
	v_mfma_f32_16x16x32_bf16 v[24:27], v[168:171], v[224:227], v[24:27]
	v_mfma_f32_16x16x32_bf16 v[12:15], v[160:163], v[232:235], v[12:15]
	v_mfma_f32_16x16x32_bf16 v[8:11], v[168:171], v[232:235], v[8:11]
	v_mfma_f32_16x16x32_bf16 v[52:55], v[172:175], v[196:199], v[52:55]
	v_mfma_f32_16x16x32_bf16 v[48:51], v[180:183], v[196:199], v[48:51]
	v_mfma_f32_16x16x32_bf16 v[36:39], v[172:175], v[212:215], v[36:39]
	v_mfma_f32_16x16x32_bf16 v[32:35], v[180:183], v[212:215], v[32:35]
	v_mfma_f32_16x16x32_bf16 v[20:23], v[172:175], v[220:223], v[20:23]
	v_mfma_f32_16x16x32_bf16 v[16:19], v[180:183], v[220:223], v[16:19]
	v_mfma_f32_16x16x32_bf16 v[4:7], v[172:175], v[228:231], v[4:7]
	v_mfma_f32_16x16x32_bf16 v[0:3], v[180:183], v[228:231], v[0:3]
	v_mfma_f32_16x16x32_bf16 v[52:55], v[176:179], v[200:203], v[52:55]
	v_mfma_f32_16x16x32_bf16 v[48:51], v[184:187], v[200:203], v[48:51]
	v_mfma_f32_16x16x32_bf16 v[36:39], v[176:179], v[216:219], v[36:39]
	v_mfma_f32_16x16x32_bf16 v[32:35], v[184:187], v[216:219], v[32:35]
	v_mfma_f32_16x16x32_bf16 v[20:23], v[176:179], v[224:227], v[20:23]
	v_mfma_f32_16x16x32_bf16 v[16:19], v[184:187], v[224:227], v[16:19]
	v_mfma_f32_16x16x32_bf16 v[4:7], v[176:179], v[232:235], v[4:7]
	v_mfma_f32_16x16x32_bf16 v[0:3], v[184:187], v[232:235], v[0:3]
	s_barrier
; #define WAIT_V(n) asm volatile("s_waitcnt vmcnt(" #n ")" ::: "memory")
; #define WAIT_L(n) asm volatile("s_waitcnt lgkmcnt(" #n ")" ::: "memory")
; #define BAR __builtin_amdgcn_s_barrier()
; #define SCHED __builtin_amdgcn_sched_barrier(0)
; #define STG_A(b, h, ptr) do { const char* _g = (ptr) + (h) * ahalf; LAS unsigned char* _l = lw + ((b) * 2 + (h)) * 16384; GLDS(_g + voa0, _l); GLDS(_g + voa1, _l + 8192); } while (0)
; #define LDA(dst, b, h) _Pragma("unroll") for (int m = 0; m < 4; ++m) _Pragma("unroll") for (int k = 0; k < 2; ++k) dst[m][k] = *(const LAS bf16x8*)(la + ((b) * 2 + (h)) * 16384 + m * 2048 + k * 1024)
; #define LDB(dst, b, h) _Pragma("unroll") for (int n = 0; n < 2; ++n) _Pragma("unroll") for (int k = 0; k < 2; ++k) dst[n][k] = *(const LAS bf16x8*)(lb + ((b) * 2 + (h)) * 16384 + n * 2048 + k * 1024)
; #define MMA(ai, bj, Af, Bf) do { __builtin_amdgcn_s_setprio(1); \
;     _Pragma("unroll") for (int m = 0; m < 4; ++m) _Pragma("unroll") for (int n = 0; n < 2; ++n) _Pragma("unroll") for (int k = 0; k < 2; ++k) \
;         acc[ai][bj][m][n] = __builtin_amdgcn_mfma_f32_16x16x32_bf16(Bf[n][k], Af[m][k], acc[ai][bj][m][n], 0, 0, 0); \
;     __builtin_amdgcn_s_setprio(0); } while (0)
; template <int BMODE, class Epi, class TileFn>
; DEV void gemm_loop(LAS unsigned char* lds, const bf16_t* __restrict__ A, int lda, const bf16_t* __restrict__ B, int ldb, int K, const Epi& epi, int t0, int tstep, int tend, const TileFn& tf) {
;     ...
;             LDB(B0, 1, 0); LDB(B1, 1, 1); SCHED; LDA(At, 1, 0); STG_A(0, 1, a2);
;             WAIT_V(8); WAIT_L(0); BAR; MMA(0, 0, At, B0); MMA(0, 1, At, B1); BAR; SCHED;
.Lkmid_688:
	ds_read_b128 v[156:159], v153 offset:32768
	ds_read_b128 v[160:163], v153 offset:33792
	ds_read_b128 v[164:167], v153 offset:34816
	ds_read_b128 v[168:171], v153 offset:35840
	ds_read_b128 v[172:175], v153 offset:49152
	ds_read_b128 v[176:179], v153 offset:50176
	ds_read_b128 v[180:183], v153 offset:51200
	ds_read_b128 v[184:187], v153 offset:52224
	s_add_u32 s28, s38, 0x88000
	s_addc_u32 s29, s39, 0
	v_readfirstlane_b32 s7, v145
	v_lshl_add_u64 v[238:239], s[28:29], 0, v[128:129]
	s_mov_b32 m0, s7
	v_readfirstlane_b32 s7, v146
	ds_read_b128 v[196:199], v154 offset:32768
	ds_read_b128 v[200:203], v154 offset:33792
	ds_read_b128 v[212:215], v154 offset:34816
	ds_read_b128 v[216:219], v154 offset:35840
	ds_read_b128 v[220:223], v154 offset:36864
	ds_read_b128 v[224:227], v154 offset:37888
	ds_read_b128 v[228:231], v154 offset:38912
	ds_read_b128 v[232:235], v154 offset:39936
	global_load_lds_dwordx4 v[238:239], off
	v_lshl_add_u64 v[238:239], s[28:29], 0, v[130:131]
	s_mov_b32 m0, s7
	s_nop 0
	global_load_lds_dwordx4 v[238:239], off
	s_waitcnt vmcnt(8)
	s_waitcnt lgkmcnt(0)
	s_barrier
	s_waitcnt lgkmcnt(0)
	v_mfma_f32_16x16x32_bf16 v[124:127], v[156:159], v[196:199], v[124:127]
	v_mfma_f32_16x16x32_bf16 v[120:123], v[164:167], v[196:199], v[120:123]
	v_mfma_f32_16x16x32_bf16 v[108:111], v[156:159], v[212:215], v[108:111]
	v_mfma_f32_16x16x32_bf16 v[104:107], v[164:167], v[212:215], v[104:107]
	v_mfma_f32_16x16x32_bf16 v[92:95], v[156:159], v[220:223], v[92:95]
	v_mfma_f32_16x16x32_bf16 v[88:91], v[164:167], v[220:223], v[88:91]
	v_mfma_f32_16x16x32_bf16 v[76:79], v[156:159], v[228:231], v[76:79]
	v_mfma_f32_16x16x32_bf16 v[72:75], v[164:167], v[228:231], v[72:75]
	v_mfma_f32_16x16x32_bf16 v[124:127], v[160:163], v[200:203], v[124:127]
	v_mfma_f32_16x16x32_bf16 v[120:123], v[168:171], v[200:203], v[120:123]
	v_mfma_f32_16x16x32_bf16 v[108:111], v[160:163], v[216:219], v[108:111]
	v_mfma_f32_16x16x32_bf16 v[104:107], v[168:171], v[216:219], v[104:107]
	v_mfma_f32_16x16x32_bf16 v[92:95], v[160:163], v[224:227], v[92:95]
	v_mfma_f32_16x16x32_bf16 v[88:91], v[168:171], v[224:227], v[88:91]
	v_mfma_f32_16x16x32_bf16 v[76:79], v[160:163], v[232:235], v[76:79]
	v_mfma_f32_16x16x32_bf16 v[72:75], v[168:171], v[232:235], v[72:75]
	v_mfma_f32_16x16x32_bf16 v[116:119], v[172:175], v[196:199], v[116:119]
	v_mfma_f32_16x16x32_bf16 v[112:115], v[180:183], v[196:199], v[112:115]
	v_mfma_f32_16x16x32_bf16 v[100:103], v[172:175], v[212:215], v[100:103]
	v_mfma_f32_16x16x32_bf16 v[96:99], v[180:183], v[212:215], v[96:99]
	v_mfma_f32_16x16x32_bf16 v[84:87], v[172:175], v[220:223], v[84:87]
	v_mfma_f32_16x16x32_bf16 v[80:83], v[180:183], v[220:223], v[80:83]
	v_mfma_f32_16x16x32_bf16 v[68:71], v[172:175], v[228:231], v[68:71]
	v_mfma_f32_16x16x32_bf16 v[64:67], v[180:183], v[228:231], v[64:67]
	v_mfma_f32_16x16x32_bf16 v[116:119], v[176:179], v[200:203], v[116:119]
	v_mfma_f32_16x16x32_bf16 v[112:115], v[184:187], v[200:203], v[112:115]
	v_mfma_f32_16x16x32_bf16 v[100:103], v[176:179], v[216:219], v[100:103]
	v_mfma_f32_16x16x32_bf16 v[96:99], v[184:187], v[216:219], v[96:99]
	v_mfma_f32_16x16x32_bf16 v[84:87], v[176:179], v[224:227], v[84:87]
	v_mfma_f32_16x16x32_bf16 v[80:83], v[184:187], v[224:227], v[80:83]
	v_mfma_f32_16x16x32_bf16 v[68:71], v[176:179], v[232:235], v[68:71]
	v_mfma_f32_16x16x32_bf16 v[64:67], v[184:187], v[232:235], v[64:67]
	s_barrier
; #define WAIT_V(n) asm volatile("s_waitcnt vmcnt(" #n ")" ::: "memory")
; #define WAIT_L(n) asm volatile("s_waitcnt lgkmcnt(" #n ")" ::: "memory")
; #define BAR __builtin_amdgcn_s_barrier()
; #define SCHED __builtin_amdgcn_sched_barrier(0)
; #define STG_A(b, h, ptr) do { const char* _g = (ptr) + (h) * ahalf; LAS unsigned char* _l = lw + ((b) * 2 + (h)) * 16384; GLDS(_g + voa0, _l); GLDS(_g + voa1, _l + 8192); } while (0)
; #define STG_B(b, h, ptr) do { const char* _g = (ptr) + (h) * bhalf; LAS unsigned char* _l = lw + 65536 + ((b) * 2 + (h)) * 16384; GLDS(_g + vob0, _l); GLDS(_g + vob1, _l + 8192); } while (0)
; #define LDA(dst, b, h) _Pragma("unroll") for (int m = 0; m < 4; ++m) _Pragma("unroll") for (int k = 0; k < 2; ++k) dst[m][k] = *(const LAS bf16x8*)(la + ((b) * 2 + (h)) * 16384 + m * 2048 + k * 1024)
; #define MMA(ai, bj, Af, Bf) do { __builtin_amdgcn_s_setprio(1); \
;     _Pragma("unroll") for (int m = 0; m < 4; ++m) _Pragma("unroll") for (int n = 0; n < 2; ++n) _Pragma("unroll") for (int k = 0; k < 2; ++k) \
;         acc[ai][bj][m][n] = __builtin_amdgcn_mfma_f32_16x16x32_bf16(Bf[n][k], Af[m][k], acc[ai][bj][m][n], 0, 0, 0); \
;     __builtin_amdgcn_s_setprio(0); } while (0)
; template <int BMODE, class Epi, class TileFn>
; DEV void gemm_loop(LAS unsigned char* lds, const bf16_t* __restrict__ A, int lda, const bf16_t* __restrict__ B, int ldb, int K, const Epi& epi, int t0, int tstep, int tend, const TileFn& tf) {
;     ...
;             LDA(At, 1, 1); STG_B(1, 0, b3); STG_B(1, 1, b3); STG_A(1, 0, a3);
;             WAIT_V(8); WAIT_L(0); BAR; MMA(1, 0, At, B0); MMA(1, 1, At, B1); BAR; SCHED;
;         }
;         if (wr == 0) BAR;
	s_add_u32 s28, s8, 0x80000
	s_addc_u32 s29, s9, 0
	v_readfirstlane_b32 s7, v147
	v_lshl_add_u64 v[238:239], s[28:29], 0, v[194:195]
	s_mov_b32 m0, s7
	v_readfirstlane_b32 s7, v148
	s_add_u32 s8, s8, 0x80800
	ds_read_b128 v[196:199], v154 offset:49152
	ds_read_b128 v[200:203], v154 offset:50176
	ds_read_b128 v[212:215], v154 offset:51200
	ds_read_b128 v[216:219], v154 offset:52224
	ds_read_b128 v[220:223], v154 offset:53248
	ds_read_b128 v[224:227], v154 offset:54272
	ds_read_b128 v[228:231], v154 offset:55296
	ds_read_b128 v[232:235], v154 offset:56320
	global_load_lds_dwordx4 v[238:239], off
	v_lshl_add_u64 v[238:239], s[28:29], 0, v[132:133]
	s_mov_b32 m0, s7
	s_addc_u32 s9, s9, 0
	v_readfirstlane_b32 s7, v151
	global_load_lds_dwordx4 v[238:239], off
	v_lshl_add_u64 v[238:239], s[8:9], 0, v[194:195]
	s_mov_b32 m0, s7
	v_readfirstlane_b32 s7, v152
	global_load_lds_dwordx4 v[238:239], off
	v_lshl_add_u64 v[238:239], s[8:9], 0, v[132:133]
	s_mov_b32 m0, s7
	v_readfirstlane_b32 s7, v149
	global_load_lds_dwordx4 v[238:239], off
	v_lshl_add_u64 v[204:205], v[204:205], 0, s[2:3]
	s_mov_b32 m0, s7
	v_readfirstlane_b32 s7, v150
	global_load_lds_dwordx4 v[204:205], off
	v_lshl_add_u64 v[204:205], v[236:237], 0, s[2:3]
	s_mov_b32 m0, s7
	s_nop 0
	global_load_lds_dwordx4 v[204:205], off
	s_waitcnt vmcnt(8)
	s_waitcnt lgkmcnt(0)
	s_barrier
	s_waitcnt lgkmcnt(0)
	v_mfma_f32_16x16x32_bf16 v[60:63], v[156:159], v[196:199], v[60:63]
	v_mfma_f32_16x16x32_bf16 v[56:59], v[164:167], v[196:199], v[56:59]
	v_mfma_f32_16x16x32_bf16 v[44:47], v[156:159], v[212:215], v[44:47]
	v_mfma_f32_16x16x32_bf16 v[40:43], v[164:167], v[212:215], v[40:43]
	v_mfma_f32_16x16x32_bf16 v[28:31], v[156:159], v[220:223], v[28:31]
	v_mfma_f32_16x16x32_bf16 v[24:27], v[164:167], v[220:223], v[24:27]
	v_mfma_f32_16x16x32_bf16 v[12:15], v[156:159], v[228:231], v[12:15]
	v_mfma_f32_16x16x32_bf16 v[8:11], v[164:167], v[228:231], v[8:11]
	v_mfma_f32_16x16x32_bf16 v[60:63], v[160:163], v[200:203], v[60:63]
	v_mfma_f32_16x16x32_bf16 v[56:59], v[168:171], v[200:203], v[56:59]
	v_mfma_f32_16x16x32_bf16 v[44:47], v[160:163], v[216:219], v[44:47]
	v_mfma_f32_16x16x32_bf16 v[40:43], v[168:171], v[216:219], v[40:43]
	v_mfma_f32_16x16x32_bf16 v[28:31], v[160:163], v[224:227], v[28:31]
	v_mfma_f32_16x16x32_bf16 v[24:27], v[168:171], v[224:227], v[24:27]
	v_mfma_f32_16x16x32_bf16 v[12:15], v[160:163], v[232:235], v[12:15]
	v_mfma_f32_16x16x32_bf16 v[8:11], v[168:171], v[232:235], v[8:11]
	v_mfma_f32_16x16x32_bf16 v[52:55], v[172:175], v[196:199], v[52:55]
	v_mfma_f32_16x16x32_bf16 v[48:51], v[180:183], v[196:199], v[48:51]
	v_mfma_f32_16x16x32_bf16 v[36:39], v[172:175], v[212:215], v[36:39]
	v_mfma_f32_16x16x32_bf16 v[32:35], v[180:183], v[212:215], v[32:35]
	v_mfma_f32_16x16x32_bf16 v[20:23], v[172:175], v[220:223], v[20:23]
	v_mfma_f32_16x16x32_bf16 v[16:19], v[180:183], v[220:223], v[16:19]
	v_mfma_f32_16x16x32_bf16 v[4:7], v[172:175], v[228:231], v[4:7]
	v_mfma_f32_16x16x32_bf16 v[0:3], v[180:183], v[228:231], v[0:3]
	v_mfma_f32_16x16x32_bf16 v[52:55], v[176:179], v[200:203], v[52:55]
	v_mfma_f32_16x16x32_bf16 v[48:51], v[184:187], v[200:203], v[48:51]
	v_mfma_f32_16x16x32_bf16 v[36:39], v[176:179], v[216:219], v[36:39]
	v_mfma_f32_16x16x32_bf16 v[32:35], v[184:187], v[216:219], v[32:35]
	v_mfma_f32_16x16x32_bf16 v[20:23], v[176:179], v[224:227], v[20:23]
	v_mfma_f32_16x16x32_bf16 v[16:19], v[184:187], v[224:227], v[16:19]
	v_mfma_f32_16x16x32_bf16 v[4:7], v[176:179], v[232:235], v[4:7]
	v_mfma_f32_16x16x32_bf16 v[0:3], v[184:187], v[232:235], v[0:3]
	s_barrier
	s_add_i32 s4, s4, 2
	s_add_u32 s0, s0, 0x100000
	s_addc_u32 s1, s1, 0
	s_add_u32 s36, s36, 0x100
	s_addc_u32 s37, s37, 0
	s_cmp_gt_u32 s4, 31
	s_cbranch_scc0 .LBB0_688
	s_setprio 0
	s_movk_i32 s0, 0x100
	v_cmp_gt_u32_e32 vcc, s0, v138
	s_and_saveexec_b64 s[0:1], vcc
	s_cbranch_execz .LBB0_691
	s_barrier

; #define LAS __attribute__((address_space(3)))
; #define WAIT_V(n) asm volatile("s_waitcnt vmcnt(" #n ")" ::: "memory")
; #define WAIT_L(n) asm volatile("s_waitcnt lgkmcnt(" #n ")" ::: "memory")
; #define BAR __builtin_amdgcn_s_barrier()
; #define SCHED __builtin_amdgcn_sched_barrier(0)
; #define STG_A(b, h, ptr) do { const char* _g = (ptr) + (h) * ahalf; LAS unsigned char* _l = lw + ((b) * 2 + (h)) * 16384; GLDS(_g + voa0, _l); GLDS(_g + voa1, _l + 8192); } while (0)
; #define STG_B(b, h, ptr) do { const char* _g = (ptr) + (h) * bhalf; LAS unsigned char* _l = lw + 65536 + ((b) * 2 + (h)) * 16384; GLDS(_g + vob0, _l); GLDS(_g + vob1, _l + 8192); } while (0)
; template <int BMODE, class Epi, class TileFn>
; DEV void gemm_loop(LAS unsigned char* lds, const bf16_t* __restrict__ A, int lda, const bf16_t* __restrict__ B, int ldb, int K, const Epi& epi, int t0, int tstep, int tend, const TileFn& tf) {
;     ...
;     if (BMODE == 0) { vob0 = (unsigned)(r0b * ldb + c0) * 2u; vob1 = vob0 + (unsigned)(64 * ldb) * 2u; bks = 128; bhalf = (size_t)128 * ldb * 2; }
;     else { vob0 = (unsigned)((c0 >> 3) * ldb + r0b) * 16u; vob1 = vob0 + 64u * 16u; bks = (size_t)ldb * 128; bhalf = 128 * 16; }
;     LAS unsigned char* lw = lds + tid * 16;
;     const int sw = swz_off(fr, fq);
;     LAS unsigned char* la = lds + wr * 8192 + sw;
;     LAS unsigned char* lb = lds + 65536 + wc * 4096 + sw;
;     int brow, bcol; tf(t0, brow, bcol);
;     const char* cA = (const char*)(A + (size_t)brow * lda);
;     const char* cB = BMODE == 0 ? (const char*)(B + (size_t)bcol * ldb) : (const char*)(B + (size_t)bcol * 8);
;     ...
;     const int nt = K / 64;
;     f32x4 acc[2][2][4][2];
; #pragma unroll
;     for (int a = 0; a < 2; ++a)
; #pragma unroll
;         for (int b = 0; b < 2; ++b)
; #pragma unroll
;             for (int m = 0; m < 4; ++m)
; #pragma unroll
;                 for (int n = 0; n < 2; ++n) acc[a][b][m][n] = (f32x4){0.f, 0.f, 0.f, 0.f};
;     bf16x8 At[4][2], B0[2][2], B1[2][2];
;     STG_B(0, 0, cB); STG_B(0, 1, cB); STG_A(0, 0, cA); STG_A(0, 1, cA);
;     if (wr == 1) BAR;
;     WAIT_V(2); BAR;
;     STG_B(1, 0, cB + bks); STG_A(1, 0, cA + 128); STG_B(1, 1, cB + bks);
;     WAIT_V(6); BAR;
;     ...
;             LDB(B0, 0, 0); LDB(B1, 0, 1); SCHED; LDA(At, 0, 0); STG_A(1, 1, a1);
;             WAIT_V(8); WAIT_L(0); BAR; MMA(0, 0, At, B0); MMA(0, 1, At, B1); BAR; SCHED;
.LBB0_770:
	s_or_b64 exec, exec, s[8:9]
	v_lshl_add_u32 v7, v4, 13, 0
	v_lshlrev_b32_e32 v4, 6, v138
	s_add_i32 s4, 0, 0x10000
	v_and_b32_e32 v5, 15, v138
	v_lshlrev_b32_e32 v6, 2, v138
	v_and_b32_e32 v4, 0x3000, v4
	s_add_u32 s8, s0, 0x400000
	v_add_u32_e32 v147, 0x18000, v139
	v_lshlrev_b32_e32 v5, 6, v5
	v_and_b32_e32 v6, 32, v6
	v_add_u32_e32 v8, s4, v4
	v_and_b32_e32 v4, 48, v138
	s_addc_u32 s9, s1, 0
	v_readfirstlane_b32 s4, v147
	v_bitop3_b32 v6, v5, v6, v4 bitop3:0x36
	v_lshl_add_u64 v[4:5], s[8:9], 0, v[194:195]
	s_mov_b32 m0, s4
	v_add_u32_e32 v148, 0x1a000, v139
	s_waitcnt vmcnt(2)
	s_barrier
	global_load_lds_dwordx4 v[4:5], off
	v_lshl_add_u64 v[4:5], s[8:9], 0, v[132:133]
	v_readfirstlane_b32 s4, v148
	v_add_u32_e32 v149, 0x8000, v139
	v_readlane_b32 s8, v253, 16
	v_mov_b32_e32 v129, v195
	s_mov_b32 m0, s4
	v_readlane_b32 s9, v253, 17
	v_readfirstlane_b32 s4, v149
	v_mov_b32_e32 v131, v195
	global_load_lds_dwordx4 v[4:5], off
	v_lshl_add_u64 v[4:5], s[8:9], 0, v[128:129]
	s_mov_b32 m0, s4
	v_add_u32_e32 v150, 0xa000, v139
	global_load_lds_dwordx4 v[4:5], off
	v_lshl_add_u64 v[4:5], s[8:9], 0, v[130:131]
	v_readfirstlane_b32 s4, v150
	s_add_u32 s8, s0, 0x400800
	v_add_u32_e32 v151, 0x1c000, v139
	s_mov_b32 m0, s4
	s_addc_u32 s9, s1, 0
	v_readfirstlane_b32 s4, v151
	v_add_u32_e32 v152, 0x1e000, v139
	global_load_lds_dwordx4 v[4:5], off
	v_lshl_add_u64 v[4:5], s[8:9], 0, v[194:195]
	s_mov_b32 m0, s4
	v_readfirstlane_b32 s4, v152
	global_load_lds_dwordx4 v[4:5], off
	v_lshl_add_u64 v[4:5], s[8:9], 0, v[132:133]
	s_mov_b32 m0, s4
	v_lshrrev_b32_e32 v2, 4, v2
	global_load_lds_dwordx4 v[4:5], off
	s_movk_i32 s4, 0x2800
	v_mul_lo_u32 v2, v2, s4
	v_or_b32_e32 v2, v3, v2
	s_movk_i32 s4, 0x280
	v_mad_u32_u24 v0, v0, s4, v2
	v_add_lshl_u32 v0, v0, v1, 1
	v_mov_b32_e32 v1, v195
	s_waitcnt vmcnt(6)
	v_lshl_add_u64 v[134:135], s[66:67], 0, v[0:1]
	v_add_u32_e32 v0, 0x14000, v0
	v_lshl_add_u64 v[136:137], s[66:67], 0, v[0:1]
	s_mov_b32 s4, -2
	s_mov_b64 s[36:37], 0x800000
	s_mov_b64 s[38:39], 0x5fc0080
	v_add_u32_e32 v153, v8, v6
	v_add_u32_e32 v154, v7, v6
	s_barrier
	v_readfirstlane_b32 s100, v188
	s_nop 3
	s_cmp_lt_u32 s100, 0x100
	s_cbranch_scc1 .Lsp_771
	s_setprio 1
.Lsp_771:
	ds_read_b128 v[156:159], v153
	ds_read_b128 v[160:163], v153 offset:1024
	ds_read_b128 v[164:167], v153 offset:2048
	ds_read_b128 v[168:171], v153 offset:3072
	ds_read_b128 v[172:175], v153 offset:16384
	ds_read_b128 v[176:179], v153 offset:17408
	ds_read_b128 v[180:183], v153 offset:18432
	ds_read_b128 v[184:187], v153 offset:19456
	s_add_u32 s8, s38, 0xfa040080
	s_addc_u32 s9, s39, -1
	s_cmp_eq_u32 s4, 6
	s_cselect_b32 s8, 0, s8
	s_cselect_b32 s9, 0, s9
	s_cselect_b32 s29, 0, s36
	s_cselect_b32 s30, 0, s37
	s_add_u32 s40, s68, s8
	s_addc_u32 s41, s69, s9
	s_add_u32 s8, s0, s29
	s_addc_u32 s9, s1, s30
	v_add_u32_e32 v155, 0xc000, v139
	v_lshl_add_u64 v[204:205], v[134:135], 0, s[38:39]
	v_readfirstlane_b32 s29, v155
	v_add_u32_e32 v155, 0xe000, v139
	s_mov_b32 m0, s29
	v_readfirstlane_b32 s29, v155
	ds_read_b128 v[196:199], v154
	ds_read_b128 v[200:203], v154 offset:1024
	ds_read_b128 v[212:215], v154 offset:2048
	ds_read_b128 v[216:219], v154 offset:3072
	ds_read_b128 v[220:223], v154 offset:4096
	ds_read_b128 v[224:227], v154 offset:5120
	ds_read_b128 v[228:231], v154 offset:6144
	ds_read_b128 v[232:235], v154 offset:7168
	global_load_lds_dwordx4 v[204:205], off
	v_lshl_add_u64 v[204:205], v[136:137], 0, s[38:39]
	s_mov_b32 m0, s29
	s_nop 0
	global_load_lds_dwordx4 v[204:205], off
	s_waitcnt vmcnt(8)
	s_waitcnt lgkmcnt(0)
	s_barrier
	s_waitcnt lgkmcnt(0)
	v_mfma_f32_16x16x32_bf16 v[124:127], v[156:159], v[196:199], 0
	v_mfma_f32_16x16x32_bf16 v[120:123], v[164:167], v[196:199], 0
	v_mfma_f32_16x16x32_bf16 v[108:111], v[156:159], v[212:215], 0
	v_mfma_f32_16x16x32_bf16 v[104:107], v[164:167], v[212:215], 0
	v_mfma_f32_16x16x32_bf16 v[92:95], v[156:159], v[220:223], 0
	v_mfma_f32_16x16x32_bf16 v[88:91], v[164:167], v[220:223], 0
	v_mfma_f32_16x16x32_bf16 v[76:79], v[156:159], v[228:231], 0
	v_mfma_f32_16x16x32_bf16 v[72:75], v[164:167], v[228:231], 0
	v_mfma_f32_16x16x32_bf16 v[124:127], v[160:163], v[200:203], v[124:127]
	v_mfma_f32_16x16x32_bf16 v[120:123], v[168:171], v[200:203], v[120:123]
	v_mfma_f32_16x16x32_bf16 v[108:111], v[160:163], v[216:219], v[108:111]
	v_mfma_f32_16x16x32_bf16 v[104:107], v[168:171], v[216:219], v[104:107]
	v_mfma_f32_16x16x32_bf16 v[92:95], v[160:163], v[224:227], v[92:95]
	v_mfma_f32_16x16x32_bf16 v[88:91], v[168:171], v[224:227], v[88:91]
	v_mfma_f32_16x16x32_bf16 v[76:79], v[160:163], v[232:235], v[76:79]
	v_mfma_f32_16x16x32_bf16 v[72:75], v[168:171], v[232:235], v[72:75]
	v_mfma_f32_16x16x32_bf16 v[116:119], v[172:175], v[196:199], 0
	v_mfma_f32_16x16x32_bf16 v[112:115], v[180:183], v[196:199], 0
	v_mfma_f32_16x16x32_bf16 v[100:103], v[172:175], v[212:215], 0
	v_mfma_f32_16x16x32_bf16 v[96:99], v[180:183], v[212:215], 0
	v_mfma_f32_16x16x32_bf16 v[84:87], v[172:175], v[220:223], 0
	v_mfma_f32_16x16x32_bf16 v[80:83], v[180:183], v[220:223], 0
	v_mfma_f32_16x16x32_bf16 v[68:71], v[172:175], v[228:231], 0
	v_mfma_f32_16x16x32_bf16 v[64:67], v[180:183], v[228:231], 0
	v_mfma_f32_16x16x32_bf16 v[116:119], v[176:179], v[200:203], v[116:119]
	v_mfma_f32_16x16x32_bf16 v[112:115], v[184:187], v[200:203], v[112:115]
	v_mfma_f32_16x16x32_bf16 v[100:103], v[176:179], v[216:219], v[100:103]
	v_mfma_f32_16x16x32_bf16 v[96:99], v[184:187], v[216:219], v[96:99]
	v_mfma_f32_16x16x32_bf16 v[84:87], v[176:179], v[224:227], v[84:87]
	v_mfma_f32_16x16x32_bf16 v[80:83], v[184:187], v[224:227], v[80:83]
	v_mfma_f32_16x16x32_bf16 v[68:71], v[176:179], v[232:235], v[68:71]
	v_mfma_f32_16x16x32_bf16 v[64:67], v[184:187], v[232:235], v[64:67]
	s_barrier
; #define WAIT_V(n) asm volatile("s_waitcnt vmcnt(" #n ")" ::: "memory")
; #define WAIT_L(n) asm volatile("s_waitcnt lgkmcnt(" #n ")" ::: "memory")
; #define BAR __builtin_amdgcn_s_barrier()
; #define SCHED __builtin_amdgcn_sched_barrier(0)
; #define STG_A(b, h, ptr) do { const char* _g = (ptr) + (h) * ahalf; LAS unsigned char* _l = lw + ((b) * 2 + (h)) * 16384; GLDS(_g + voa0, _l); GLDS(_g + voa1, _l + 8192); } while (0)
; #define STG_B(b, h, ptr) do { const char* _g = (ptr) + (h) * bhalf; LAS unsigned char* _l = lw + 65536 + ((b) * 2 + (h)) * 16384; GLDS(_g + vob0, _l); GLDS(_g + vob1, _l + 8192); } while (0)
; #define LDA(dst, b, h) _Pragma("unroll") for (int m = 0; m < 4; ++m) _Pragma("unroll") for (int k = 0; k < 2; ++k) dst[m][k] = *(const LAS bf16x8*)(la + ((b) * 2 + (h)) * 16384 + m * 2048 + k * 1024)
; #define LDB(dst, b, h) _Pragma("unroll") for (int n = 0; n < 2; ++n) _Pragma("unroll") for (int k = 0; k < 2; ++k) dst[n][k] = *(const LAS bf16x8*)(lb + ((b) * 2 + (h)) * 16384 + n * 2048 + k * 1024)
; #define MMA(ai, bj, Af, Bf) do { __builtin_amdgcn_s_setprio(1); \
;     _Pragma("unroll") for (int m = 0; m < 4; ++m) _Pragma("unroll") for (int n = 0; n < 2; ++n) _Pragma("unroll") for (int k = 0; k < 2; ++k) \
;         acc[ai][bj][m][n] = __builtin_amdgcn_mfma_f32_16x16x32_bf16(Bf[n][k], Af[m][k], acc[ai][bj][m][n], 0, 0, 0); \
;     __builtin_amdgcn_s_setprio(0); } while (0)
; template <int BMODE, class Epi, class TileFn>
; DEV void gemm_loop(LAS unsigned char* lds, const bf16_t* __restrict__ A, int lda, const bf16_t* __restrict__ B, int ldb, int K, const Epi& epi, int t0, int tstep, int tend, const TileFn& tf) {
;     ...
;             LDB(B0, 0, 0); LDB(B1, 0, 1); SCHED; LDA(At, 0, 0); STG_A(1, 1, a1);
;             WAIT_V(8); WAIT_L(0); BAR; MMA(0, 0, At, B0); MMA(0, 1, At, B1); BAR; SCHED;
;             LDA(At, 0, 1); STG_B(0, 0, b2); STG_B(0, 1, b2); STG_A(0, 0, a2);
;             WAIT_V(8); WAIT_L(0); BAR; MMA(1, 0, At, B0); MMA(1, 1, At, B1); BAR; SCHED;
	v_readfirstlane_b32 s29, v140
	v_lshl_add_u64 v[204:205], s[8:9], 0, v[194:195]
	s_mov_b32 m0, s29
	v_readfirstlane_b32 s29, v141
	ds_read_b128 v[196:199], v154 offset:16384
	ds_read_b128 v[200:203], v154 offset:17408
	ds_read_b128 v[212:215], v154 offset:18432
	ds_read_b128 v[216:219], v154 offset:19456
	ds_read_b128 v[220:223], v154 offset:20480
	ds_read_b128 v[224:227], v154 offset:21504
	ds_read_b128 v[228:231], v154 offset:22528
	ds_read_b128 v[232:235], v154 offset:23552
	global_load_lds_dwordx4 v[204:205], off
	v_lshl_add_u64 v[236:237], s[8:9], 0, v[132:133]
	s_mov_b32 m0, s29
	v_readfirstlane_b32 s29, v142
	global_load_lds_dwordx4 v[236:237], off
	v_lshl_add_u64 v[204:205], v[204:205], 0, s[86:87]
	s_mov_b32 m0, s29
	v_readfirstlane_b32 s29, v143
	global_load_lds_dwordx4 v[204:205], off
	v_lshl_add_u64 v[204:205], v[236:237], 0, s[86:87]
	s_mov_b32 m0, s29
	v_readfirstlane_b32 s29, v139
	global_load_lds_dwordx4 v[204:205], off
	v_lshl_add_u64 v[204:205], s[40:41], 0, v[128:129]
	s_mov_b32 m0, s29
	v_readfirstlane_b32 s29, v144
	global_load_lds_dwordx4 v[204:205], off
	v_lshl_add_u64 v[236:237], s[40:41], 0, v[130:131]
	s_mov_b32 m0, s29
	s_nop 0
	global_load_lds_dwordx4 v[236:237], off
	s_waitcnt vmcnt(8)
	s_waitcnt lgkmcnt(0)
	s_barrier
	s_waitcnt lgkmcnt(0)
	v_mfma_f32_16x16x32_bf16 v[60:63], v[156:159], v[196:199], 0
	v_mfma_f32_16x16x32_bf16 v[56:59], v[164:167], v[196:199], 0
	v_mfma_f32_16x16x32_bf16 v[44:47], v[156:159], v[212:215], 0
	v_mfma_f32_16x16x32_bf16 v[40:43], v[164:167], v[212:215], 0
	v_mfma_f32_16x16x32_bf16 v[28:31], v[156:159], v[220:223], 0
	v_mfma_f32_16x16x32_bf16 v[24:27], v[164:167], v[220:223], 0
	v_mfma_f32_16x16x32_bf16 v[12:15], v[156:159], v[228:231], 0
	v_mfma_f32_16x16x32_bf16 v[8:11], v[164:167], v[228:231], 0
	v_mfma_f32_16x16x32_bf16 v[60:63], v[160:163], v[200:203], v[60:63]
	v_mfma_f32_16x16x32_bf16 v[56:59], v[168:171], v[200:203], v[56:59]
	v_mfma_f32_16x16x32_bf16 v[44:47], v[160:163], v[216:219], v[44:47]
	v_mfma_f32_16x16x32_bf16 v[40:43], v[168:171], v[216:219], v[40:43]
	v_mfma_f32_16x16x32_bf16 v[28:31], v[160:163], v[224:227], v[28:31]
	v_mfma_f32_16x16x32_bf16 v[24:27], v[168:171], v[224:227], v[24:27]
	v_mfma_f32_16x16x32_bf16 v[12:15], v[160:163], v[232:235], v[12:15]
	v_mfma_f32_16x16x32_bf16 v[8:11], v[168:171], v[232:235], v[8:11]
	v_mfma_f32_16x16x32_bf16 v[52:55], v[172:175], v[196:199], 0
	v_mfma_f32_16x16x32_bf16 v[48:51], v[180:183], v[196:199], 0
	v_mfma_f32_16x16x32_bf16 v[36:39], v[172:175], v[212:215], 0
	v_mfma_f32_16x16x32_bf16 v[32:35], v[180:183], v[212:215], 0
	v_mfma_f32_16x16x32_bf16 v[20:23], v[172:175], v[220:223], 0
	v_mfma_f32_16x16x32_bf16 v[16:19], v[180:183], v[220:223], 0
	v_mfma_f32_16x16x32_bf16 v[4:7], v[172:175], v[228:231], 0
	v_mfma_f32_16x16x32_bf16 v[0:3], v[180:183], v[228:231], 0
	v_mfma_f32_16x16x32_bf16 v[52:55], v[176:179], v[200:203], v[52:55]
	v_mfma_f32_16x16x32_bf16 v[48:51], v[184:187], v[200:203], v[48:51]
	v_mfma_f32_16x16x32_bf16 v[36:39], v[176:179], v[216:219], v[36:39]
	v_mfma_f32_16x16x32_bf16 v[32:35], v[184:187], v[216:219], v[32:35]
	v_mfma_f32_16x16x32_bf16 v[20:23], v[176:179], v[224:227], v[20:23]
	v_mfma_f32_16x16x32_bf16 v[16:19], v[184:187], v[224:227], v[16:19]
	v_mfma_f32_16x16x32_bf16 v[4:7], v[176:179], v[232:235], v[4:7]
	v_mfma_f32_16x16x32_bf16 v[0:3], v[184:187], v[232:235], v[0:3]
	s_barrier
	s_branch .Lkmid_771
.LBB0_771:
	ds_read_b128 v[156:159], v153
	ds_read_b128 v[160:163], v153 offset:1024
	ds_read_b128 v[164:167], v153 offset:2048
	ds_read_b128 v[168:171], v153 offset:3072
	ds_read_b128 v[172:175], v153 offset:16384
	ds_read_b128 v[176:179], v153 offset:17408
	ds_read_b128 v[180:183], v153 offset:18432
	ds_read_b128 v[184:187], v153 offset:19456
	s_add_u32 s8, s38, 0xfa040080
	s_addc_u32 s9, s39, -1
	s_cmp_eq_u32 s4, 6
	s_cselect_b32 s8, 0, s8
	s_cselect_b32 s9, 0, s9
	s_cselect_b32 s29, 0, s36
	s_cselect_b32 s30, 0, s37
	s_add_u32 s40, s68, s8
	s_addc_u32 s41, s69, s9
	s_add_u32 s8, s0, s29
	s_addc_u32 s9, s1, s30
	v_add_u32_e32 v155, 0xc000, v139
	v_lshl_add_u64 v[204:205], v[134:135], 0, s[38:39]
	v_readfirstlane_b32 s29, v155
	v_add_u32_e32 v155, 0xe000, v139
	s_mov_b32 m0, s29
	v_readfirstlane_b32 s29, v155
	ds_read_b128 v[196:199], v154
	ds_read_b128 v[200:203], v154 offset:1024
	ds_read_b128 v[212:215], v154 offset:2048
	ds_read_b128 v[216:219], v154 offset:3072
	ds_read_b128 v[220:223], v154 offset:4096
	ds_read_b128 v[224:227], v154 offset:5120
	ds_read_b128 v[228:231], v154 offset:6144
	ds_read_b128 v[232:235], v154 offset:7168
	global_load_lds_dwordx4 v[204:205], off
	v_lshl_add_u64 v[204:205], v[136:137], 0, s[38:39]
	s_mov_b32 m0, s29
	s_nop 0
	global_load_lds_dwordx4 v[204:205], off
	s_waitcnt vmcnt(8)
	s_waitcnt lgkmcnt(0)
	s_barrier
; #define WAIT_V(n) asm volatile("s_waitcnt vmcnt(" #n ")" ::: "memory")
; #define WAIT_L(n) asm volatile("s_waitcnt lgkmcnt(" #n ")" ::: "memory")
; #define BAR __builtin_amdgcn_s_barrier()
; #define SCHED __builtin_amdgcn_sched_barrier(0)
; #define STG_A(b, h, ptr) do { const char* _g = (ptr) + (h) * ahalf; LAS unsigned char* _l = lw + ((b) * 2 + (h)) * 16384; GLDS(_g + voa0, _l); GLDS(_g + voa1, _l + 8192); } while (0)
; #define STG_B(b, h, ptr) do { const char* _g = (ptr) + (h) * bhalf; LAS unsigned char* _l = lw + 65536 + ((b) * 2 + (h)) * 16384; GLDS(_g + vob0, _l); GLDS(_g + vob1, _l + 8192); } while (0)
; #define LDA(dst, b, h) _Pragma("unroll") for (int m = 0; m < 4; ++m) _Pragma("unroll") for (int k = 0; k < 2; ++k) dst[m][k] = *(const LAS bf16x8*)(la + ((b) * 2 + (h)) * 16384 + m * 2048 + k * 1024)
; #define MMA(ai, bj, Af, Bf) do { __builtin_amdgcn_s_setprio(1); \
;     _Pragma("unroll") for (int m = 0; m < 4; ++m) _Pragma("unroll") for (int n = 0; n < 2; ++n) _Pragma("unroll") for (int k = 0; k < 2; ++k) \
;         acc[ai][bj][m][n] = __builtin_amdgcn_mfma_f32_16x16x32_bf16(Bf[n][k], Af[m][k], acc[ai][bj][m][n], 0, 0, 0); \
;     __builtin_amdgcn_s_setprio(0); } while (0)
; template <int BMODE, class Epi, class TileFn>
; DEV void gemm_loop(LAS unsigned char* lds, const bf16_t* __restrict__ A, int lda, const bf16_t* __restrict__ B, int ldb, int K, const Epi& epi, int t0, int tstep, int tend, const TileFn& tf) {
;     ...
;             WAIT_V(8); WAIT_L(0); BAR; MMA(0, 0, At, B0); MMA(0, 1, At, B1); BAR; SCHED;
;             LDA(At, 0, 1); STG_B(0, 0, b2); STG_B(0, 1, b2); STG_A(0, 0, a2);
;             WAIT_V(8); WAIT_L(0); BAR; MMA(1, 0, At, B0); MMA(1, 1, At, B1); BAR; SCHED;
	s_waitcnt lgkmcnt(0)
	v_mfma_f32_16x16x32_bf16 v[124:127], v[156:159], v[196:199], v[124:127]
	v_mfma_f32_16x16x32_bf16 v[120:123], v[164:167], v[196:199], v[120:123]
	v_mfma_f32_16x16x32_bf16 v[108:111], v[156:159], v[212:215], v[108:111]
	v_mfma_f32_16x16x32_bf16 v[104:107], v[164:167], v[212:215], v[104:107]
	v_mfma_f32_16x16x32_bf16 v[92:95], v[156:159], v[220:223], v[92:95]
	v_mfma_f32_16x16x32_bf16 v[88:91], v[164:167], v[220:223], v[88:91]
	v_mfma_f32_16x16x32_bf16 v[76:79], v[156:159], v[228:231], v[76:79]
	v_mfma_f32_16x16x32_bf16 v[72:75], v[164:167], v[228:231], v[72:75]
	v_mfma_f32_16x16x32_bf16 v[124:127], v[160:163], v[200:203], v[124:127]
	v_mfma_f32_16x16x32_bf16 v[120:123], v[168:171], v[200:203], v[120:123]
	v_mfma_f32_16x16x32_bf16 v[108:111], v[160:163], v[216:219], v[108:111]
	v_mfma_f32_16x16x32_bf16 v[104:107], v[168:171], v[216:219], v[104:107]
	v_mfma_f32_16x16x32_bf16 v[92:95], v[160:163], v[224:227], v[92:95]
	v_mfma_f32_16x16x32_bf16 v[88:91], v[168:171], v[224:227], v[88:91]
	v_mfma_f32_16x16x32_bf16 v[76:79], v[160:163], v[232:235], v[76:79]
	v_mfma_f32_16x16x32_bf16 v[72:75], v[168:171], v[232:235], v[72:75]
	v_mfma_f32_16x16x32_bf16 v[116:119], v[172:175], v[196:199], v[116:119]
	v_mfma_f32_16x16x32_bf16 v[112:115], v[180:183], v[196:199], v[112:115]
	v_mfma_f32_16x16x32_bf16 v[100:103], v[172:175], v[212:215], v[100:103]
	v_mfma_f32_16x16x32_bf16 v[96:99], v[180:183], v[212:215], v[96:99]
	v_mfma_f32_16x16x32_bf16 v[84:87], v[172:175], v[220:223], v[84:87]
	v_mfma_f32_16x16x32_bf16 v[80:83], v[180:183], v[220:223], v[80:83]
	v_mfma_f32_16x16x32_bf16 v[68:71], v[172:175], v[228:231], v[68:71]
	v_mfma_f32_16x16x32_bf16 v[64:67], v[180:183], v[228:231], v[64:67]
	v_mfma_f32_16x16x32_bf16 v[116:119], v[176:179], v[200:203], v[116:119]
	v_mfma_f32_16x16x32_bf16 v[112:115], v[184:187], v[200:203], v[112:115]
	v_mfma_f32_16x16x32_bf16 v[100:103], v[176:179], v[216:219], v[100:103]
	v_mfma_f32_16x16x32_bf16 v[96:99], v[184:187], v[216:219], v[96:99]
	v_mfma_f32_16x16x32_bf16 v[84:87], v[176:179], v[224:227], v[84:87]
	v_mfma_f32_16x16x32_bf16 v[80:83], v[184:187], v[224:227], v[80:83]
	v_mfma_f32_16x16x32_bf16 v[68:71], v[176:179], v[232:235], v[68:71]
	v_mfma_f32_16x16x32_bf16 v[64:67], v[184:187], v[232:235], v[64:67]
	s_barrier
	v_readfirstlane_b32 s29, v140
	v_lshl_add_u64 v[204:205], s[8:9], 0, v[194:195]
	s_mov_b32 m0, s29
	v_readfirstlane_b32 s29, v141
	ds_read_b128 v[196:199], v154 offset:16384
	ds_read_b128 v[200:203], v154 offset:17408
	ds_read_b128 v[212:215], v154 offset:18432
	ds_read_b128 v[216:219], v154 offset:19456
	ds_read_b128 v[220:223], v154 offset:20480
	ds_read_b128 v[224:227], v154 offset:21504
	ds_read_b128 v[228:231], v154 offset:22528
	ds_read_b128 v[232:235], v154 offset:23552
	global_load_lds_dwordx4 v[204:205], off
	v_lshl_add_u64 v[236:237], s[8:9], 0, v[132:133]
	s_mov_b32 m0, s29
	v_readfirstlane_b32 s29, v142
	global_load_lds_dwordx4 v[236:237], off
	v_lshl_add_u64 v[204:205], v[204:205], 0, s[86:87]
	s_mov_b32 m0, s29
	v_readfirstlane_b32 s29, v143
	global_load_lds_dwordx4 v[204:205], off
	v_lshl_add_u64 v[204:205], v[236:237], 0, s[86:87]
	s_mov_b32 m0, s29
	v_readfirstlane_b32 s29, v139
	global_load_lds_dwordx4 v[204:205], off
	v_lshl_add_u64 v[204:205], s[40:41], 0, v[128:129]
	s_mov_b32 m0, s29
	v_readfirstlane_b32 s29, v144
	global_load_lds_dwordx4 v[204:205], off
	v_lshl_add_u64 v[236:237], s[40:41], 0, v[130:131]
	s_mov_b32 m0, s29
	s_nop 0
	global_load_lds_dwordx4 v[236:237], off
	s_waitcnt vmcnt(8)
	s_waitcnt lgkmcnt(0)
	s_barrier
	s_waitcnt lgkmcnt(0)
	v_mfma_f32_16x16x32_bf16 v[60:63], v[156:159], v[196:199], v[60:63]
	v_mfma_f32_16x16x32_bf16 v[56:59], v[164:167], v[196:199], v[56:59]
	v_mfma_f32_16x16x32_bf16 v[44:47], v[156:159], v[212:215], v[44:47]
	v_mfma_f32_16x16x32_bf16 v[40:43], v[164:167], v[212:215], v[40:43]
	v_mfma_f32_16x16x32_bf16 v[28:31], v[156:159], v[220:223], v[28:31]
	v_mfma_f32_16x16x32_bf16 v[24:27], v[164:167], v[220:223], v[24:27]
	v_mfma_f32_16x16x32_bf16 v[12:15], v[156:159], v[228:231], v[12:15]
	v_mfma_f32_16x16x32_bf16 v[8:11], v[164:167], v[228:231], v[8:11]
	v_mfma_f32_16x16x32_bf16 v[60:63], v[160:163], v[200:203], v[60:63]
	v_mfma_f32_16x16x32_bf16 v[56:59], v[168:171], v[200:203], v[56:59]
	v_mfma_f32_16x16x32_bf16 v[44:47], v[160:163], v[216:219], v[44:47]
	v_mfma_f32_16x16x32_bf16 v[40:43], v[168:171], v[216:219], v[40:43]
	v_mfma_f32_16x16x32_bf16 v[28:31], v[160:163], v[224:227], v[28:31]
	v_mfma_f32_16x16x32_bf16 v[24:27], v[168:171], v[224:227], v[24:27]
	v_mfma_f32_16x16x32_bf16 v[12:15], v[160:163], v[232:235], v[12:15]
	v_mfma_f32_16x16x32_bf16 v[8:11], v[168:171], v[232:235], v[8:11]
	v_mfma_f32_16x16x32_bf16 v[52:55], v[172:175], v[196:199], v[52:55]
	v_mfma_f32_16x16x32_bf16 v[48:51], v[180:183], v[196:199], v[48:51]
	v_mfma_f32_16x16x32_bf16 v[36:39], v[172:175], v[212:215], v[36:39]
	v_mfma_f32_16x16x32_bf16 v[32:35], v[180:183], v[212:215], v[32:35]
	v_mfma_f32_16x16x32_bf16 v[20:23], v[172:175], v[220:223], v[20:23]
	v_mfma_f32_16x16x32_bf16 v[16:19], v[180:183], v[220:223], v[16:19]
	v_mfma_f32_16x16x32_bf16 v[4:7], v[172:175], v[228:231], v[4:7]
	v_mfma_f32_16x16x32_bf16 v[0:3], v[180:183], v[228:231], v[0:3]
	v_mfma_f32_16x16x32_bf16 v[52:55], v[176:179], v[200:203], v[52:55]
	v_mfma_f32_16x16x32_bf16 v[48:51], v[184:187], v[200:203], v[48:51]
	v_mfma_f32_16x16x32_bf16 v[36:39], v[176:179], v[216:219], v[36:39]
	v_mfma_f32_16x16x32_bf16 v[32:35], v[184:187], v[216:219], v[32:35]
	v_mfma_f32_16x16x32_bf16 v[20:23], v[176:179], v[224:227], v[20:23]
	v_mfma_f32_16x16x32_bf16 v[16:19], v[184:187], v[224:227], v[16:19]
	v_mfma_f32_16x16x32_bf16 v[4:7], v[176:179], v[232:235], v[4:7]
	v_mfma_f32_16x16x32_bf16 v[0:3], v[184:187], v[232:235], v[0:3]
	s_barrier
; #define WAIT_V(n) asm volatile("s_waitcnt vmcnt(" #n ")" ::: "memory")
; #define WAIT_L(n) asm volatile("s_waitcnt lgkmcnt(" #n ")" ::: "memory")
; #define BAR __builtin_amdgcn_s_barrier()
; #define SCHED __builtin_amdgcn_sched_barrier(0)
; #define STG_A(b, h, ptr) do { const char* _g = (ptr) + (h) * ahalf; LAS unsigned char* _l = lw + ((b) * 2 + (h)) * 16384; GLDS(_g + voa0, _l); GLDS(_g + voa1, _l + 8192); } while (0)
; #define LDA(dst, b, h) _Pragma("unroll") for (int m = 0; m < 4; ++m) _Pragma("unroll") for (int k = 0; k < 2; ++k) dst[m][k] = *(const LAS bf16x8*)(la + ((b) * 2 + (h)) * 16384 + m * 2048 + k * 1024)
; #define LDB(dst, b, h) _Pragma("unroll") for (int n = 0; n < 2; ++n) _Pragma("unroll") for (int k = 0; k < 2; ++k) dst[n][k] = *(const LAS bf16x8*)(lb + ((b) * 2 + (h)) * 16384 + n * 2048 + k * 1024)
; #define MMA(ai, bj, Af, Bf) do { __builtin_amdgcn_s_setprio(1); \
;     _Pragma("unroll") for (int m = 0; m < 4; ++m) _Pragma("unroll") for (int n = 0; n < 2; ++n) _Pragma("unroll") for (int k = 0; k < 2; ++k) \
;         acc[ai][bj][m][n] = __builtin_amdgcn_mfma_f32_16x16x32_bf16(Bf[n][k], Af[m][k], acc[ai][bj][m][n], 0, 0, 0); \
;     __builtin_amdgcn_s_setprio(0); } while (0)
; template <int BMODE, class Epi, class TileFn>
; DEV void gemm_loop(LAS unsigned char* lds, const bf16_t* __restrict__ A, int lda, const bf16_t* __restrict__ B, int ldb, int K, const Epi& epi, int t0, int tstep, int tend, const TileFn& tf) {
;     ...
;             LDB(B0, 1, 0); LDB(B1, 1, 1); SCHED; LDA(At, 1, 0); STG_A(0, 1, a2);
;             WAIT_V(8); WAIT_L(0); BAR; MMA(0, 0, At, B0); MMA(0, 1, At, B1); BAR; SCHED;
.Lkmid_771:
	ds_read_b128 v[156:159], v153 offset:32768
	ds_read_b128 v[160:163], v153 offset:33792
	ds_read_b128 v[164:167], v153 offset:34816
	ds_read_b128 v[168:171], v153 offset:35840
	ds_read_b128 v[172:175], v153 offset:49152
	ds_read_b128 v[176:179], v153 offset:50176
	ds_read_b128 v[180:183], v153 offset:51200
	ds_read_b128 v[184:187], v153 offset:52224
	s_add_u32 s30, s40, 0x28000
	s_addc_u32 s31, s41, 0
	v_readfirstlane_b32 s29, v145
	v_lshl_add_u64 v[238:239], s[30:31], 0, v[128:129]
	s_mov_b32 m0, s29
	v_readfirstlane_b32 s29, v146
	ds_read_b128 v[196:199], v154 offset:32768
	ds_read_b128 v[200:203], v154 offset:33792
	ds_read_b128 v[212:215], v154 offset:34816
	ds_read_b128 v[216:219], v154 offset:35840
	ds_read_b128 v[220:223], v154 offset:36864
	ds_read_b128 v[224:227], v154 offset:37888
	ds_read_b128 v[228:231], v154 offset:38912
	ds_read_b128 v[232:235], v154 offset:39936
	global_load_lds_dwordx4 v[238:239], off
	v_lshl_add_u64 v[238:239], s[30:31], 0, v[130:131]
	s_mov_b32 m0, s29
	s_nop 0
	global_load_lds_dwordx4 v[238:239], off
	s_waitcnt vmcnt(8)
	s_waitcnt lgkmcnt(0)
	s_barrier
	s_waitcnt lgkmcnt(0)
	v_mfma_f32_16x16x32_bf16 v[124:127], v[156:159], v[196:199], v[124:127]
	v_mfma_f32_16x16x32_bf16 v[120:123], v[164:167], v[196:199], v[120:123]
	v_mfma_f32_16x16x32_bf16 v[108:111], v[156:159], v[212:215], v[108:111]
	v_mfma_f32_16x16x32_bf16 v[104:107], v[164:167], v[212:215], v[104:107]
	v_mfma_f32_16x16x32_bf16 v[92:95], v[156:159], v[220:223], v[92:95]
	v_mfma_f32_16x16x32_bf16 v[88:91], v[164:167], v[220:223], v[88:91]
	v_mfma_f32_16x16x32_bf16 v[76:79], v[156:159], v[228:231], v[76:79]
	v_mfma_f32_16x16x32_bf16 v[72:75], v[164:167], v[228:231], v[72:75]
	v_mfma_f32_16x16x32_bf16 v[124:127], v[160:163], v[200:203], v[124:127]
	v_mfma_f32_16x16x32_bf16 v[120:123], v[168:171], v[200:203], v[120:123]
	v_mfma_f32_16x16x32_bf16 v[108:111], v[160:163], v[216:219], v[108:111]
	v_mfma_f32_16x16x32_bf16 v[104:107], v[168:171], v[216:219], v[104:107]
	v_mfma_f32_16x16x32_bf16 v[92:95], v[160:163], v[224:227], v[92:95]
	v_mfma_f32_16x16x32_bf16 v[88:91], v[168:171], v[224:227], v[88:91]
	v_mfma_f32_16x16x32_bf16 v[76:79], v[160:163], v[232:235], v[76:79]
	v_mfma_f32_16x16x32_bf16 v[72:75], v[168:171], v[232:235], v[72:75]
	v_mfma_f32_16x16x32_bf16 v[116:119], v[172:175], v[196:199], v[116:119]
	v_mfma_f32_16x16x32_bf16 v[112:115], v[180:183], v[196:199], v[112:115]
	v_mfma_f32_16x16x32_bf16 v[100:103], v[172:175], v[212:215], v[100:103]
	v_mfma_f32_16x16x32_bf16 v[96:99], v[180:183], v[212:215], v[96:99]
	v_mfma_f32_16x16x32_bf16 v[84:87], v[172:175], v[220:223], v[84:87]
	v_mfma_f32_16x16x32_bf16 v[80:83], v[180:183], v[220:223], v[80:83]
	v_mfma_f32_16x16x32_bf16 v[68:71], v[172:175], v[228:231], v[68:71]
	v_mfma_f32_16x16x32_bf16 v[64:67], v[180:183], v[228:231], v[64:67]
	v_mfma_f32_16x16x32_bf16 v[116:119], v[176:179], v[200:203], v[116:119]
	v_mfma_f32_16x16x32_bf16 v[112:115], v[184:187], v[200:203], v[112:115]
	v_mfma_f32_16x16x32_bf16 v[100:103], v[176:179], v[216:219], v[100:103]
	v_mfma_f32_16x16x32_bf16 v[96:99], v[184:187], v[216:219], v[96:99]
	v_mfma_f32_16x16x32_bf16 v[84:87], v[176:179], v[224:227], v[84:87]
	v_mfma_f32_16x16x32_bf16 v[80:83], v[184:187], v[224:227], v[80:83]
	v_mfma_f32_16x16x32_bf16 v[68:71], v[176:179], v[232:235], v[68:71]
	v_mfma_f32_16x16x32_bf16 v[64:67], v[184:187], v[232:235], v[64:67]
	s_barrier
; #define WAIT_V(n) asm volatile("s_waitcnt vmcnt(" #n ")" ::: "memory")
; #define WAIT_L(n) asm volatile("s_waitcnt lgkmcnt(" #n ")" ::: "memory")
; #define BAR __builtin_amdgcn_s_barrier()
; #define SCHED __builtin_amdgcn_sched_barrier(0)
; #define STG_A(b, h, ptr) do { const char* _g = (ptr) + (h) * ahalf; LAS unsigned char* _l = lw + ((b) * 2 + (h)) * 16384; GLDS(_g + voa0, _l); GLDS(_g + voa1, _l + 8192); } while (0)
; #define STG_B(b, h, ptr) do { const char* _g = (ptr) + (h) * bhalf; LAS unsigned char* _l = lw + 65536 + ((b) * 2 + (h)) * 16384; GLDS(_g + vob0, _l); GLDS(_g + vob1, _l + 8192); } while (0)
; #define LDA(dst, b, h) _Pragma("unroll") for (int m = 0; m < 4; ++m) _Pragma("unroll") for (int k = 0; k < 2; ++k) dst[m][k] = *(const LAS bf16x8*)(la + ((b) * 2 + (h)) * 16384 + m * 2048 + k * 1024)
; #define MMA(ai, bj, Af, Bf) do { __builtin_amdgcn_s_setprio(1); \
;     _Pragma("unroll") for (int m = 0; m < 4; ++m) _Pragma("unroll") for (int n = 0; n < 2; ++n) _Pragma("unroll") for (int k = 0; k < 2; ++k) \
;         acc[ai][bj][m][n] = __builtin_amdgcn_mfma_f32_16x16x32_bf16(Bf[n][k], Af[m][k], acc[ai][bj][m][n], 0, 0, 0); \
;     __builtin_amdgcn_s_setprio(0); } while (0)
; template <int BMODE, class Epi, class TileFn>
; DEV void gemm_loop(LAS unsigned char* lds, const bf16_t* __restrict__ A, int lda, const bf16_t* __restrict__ B, int ldb, int K, const Epi& epi, int t0, int tstep, int tend, const TileFn& tf) {
;     ...
;             LDA(At, 1, 1); STG_B(1, 0, b3); STG_B(1, 1, b3); STG_A(1, 0, a3);
;             WAIT_V(8); WAIT_L(0); BAR; MMA(1, 0, At, B0); MMA(1, 1, At, B1); BAR; SCHED;
;         }
;         if (wr == 0) BAR;
	s_add_u32 s30, s8, 0x400000
	s_addc_u32 s31, s9, 0
	v_readfirstlane_b32 s29, v147
	v_lshl_add_u64 v[238:239], s[30:31], 0, v[194:195]
	s_mov_b32 m0, s29
	v_readfirstlane_b32 s29, v148
	s_add_u32 s8, s8, 0x400800
	ds_read_b128 v[196:199], v154 offset:49152
	ds_read_b128 v[200:203], v154 offset:50176
	ds_read_b128 v[212:215], v154 offset:51200
	ds_read_b128 v[216:219], v154 offset:52224
	ds_read_b128 v[220:223], v154 offset:53248
	ds_read_b128 v[224:227], v154 offset:54272
	ds_read_b128 v[228:231], v154 offset:55296
	ds_read_b128 v[232:235], v154 offset:56320
	global_load_lds_dwordx4 v[238:239], off
	v_lshl_add_u64 v[238:239], s[30:31], 0, v[132:133]
	s_mov_b32 m0, s29
	s_addc_u32 s9, s9, 0
	v_readfirstlane_b32 s29, v151
	global_load_lds_dwordx4 v[238:239], off
	v_lshl_add_u64 v[238:239], s[8:9], 0, v[194:195]
	s_mov_b32 m0, s29
	v_lshl_add_u64 v[204:205], v[204:205], 0, s[2:3]
	global_load_lds_dwordx4 v[238:239], off
	v_lshl_add_u64 v[238:239], s[8:9], 0, v[132:133]
	v_readfirstlane_b32 s8, v152
	s_mov_b32 m0, s8
	v_readfirstlane_b32 s8, v149
	global_load_lds_dwordx4 v[238:239], off
	s_mov_b32 m0, s8
	v_readfirstlane_b32 s8, v150
	global_load_lds_dwordx4 v[204:205], off
	v_lshl_add_u64 v[204:205], v[236:237], 0, s[2:3]
	s_mov_b32 m0, s8
	s_nop 0
	global_load_lds_dwordx4 v[204:205], off
	s_waitcnt vmcnt(8)
	s_waitcnt lgkmcnt(0)
	s_barrier
	s_waitcnt lgkmcnt(0)
	v_mfma_f32_16x16x32_bf16 v[60:63], v[156:159], v[196:199], v[60:63]
	v_mfma_f32_16x16x32_bf16 v[56:59], v[164:167], v[196:199], v[56:59]
	v_mfma_f32_16x16x32_bf16 v[44:47], v[156:159], v[212:215], v[44:47]
	v_mfma_f32_16x16x32_bf16 v[40:43], v[164:167], v[212:215], v[40:43]
	v_mfma_f32_16x16x32_bf16 v[28:31], v[156:159], v[220:223], v[28:31]
	v_mfma_f32_16x16x32_bf16 v[24:27], v[164:167], v[220:223], v[24:27]
	v_mfma_f32_16x16x32_bf16 v[12:15], v[156:159], v[228:231], v[12:15]
	v_mfma_f32_16x16x32_bf16 v[8:11], v[164:167], v[228:231], v[8:11]
	v_mfma_f32_16x16x32_bf16 v[60:63], v[160:163], v[200:203], v[60:63]
	v_mfma_f32_16x16x32_bf16 v[56:59], v[168:171], v[200:203], v[56:59]
	v_mfma_f32_16x16x32_bf16 v[44:47], v[160:163], v[216:219], v[44:47]
	v_mfma_f32_16x16x32_bf16 v[40:43], v[168:171], v[216:219], v[40:43]
	v_mfma_f32_16x16x32_bf16 v[28:31], v[160:163], v[224:227], v[28:31]
	v_mfma_f32_16x16x32_bf16 v[24:27], v[168:171], v[224:227], v[24:27]
	v_mfma_f32_16x16x32_bf16 v[12:15], v[160:163], v[232:235], v[12:15]
	v_mfma_f32_16x16x32_bf16 v[8:11], v[168:171], v[232:235], v[8:11]
	v_mfma_f32_16x16x32_bf16 v[52:55], v[172:175], v[196:199], v[52:55]
	v_mfma_f32_16x16x32_bf16 v[48:51], v[180:183], v[196:199], v[48:51]
	v_mfma_f32_16x16x32_bf16 v[36:39], v[172:175], v[212:215], v[36:39]
	v_mfma_f32_16x16x32_bf16 v[32:35], v[180:183], v[212:215], v[32:35]
	v_mfma_f32_16x16x32_bf16 v[20:23], v[172:175], v[220:223], v[20:23]
	v_mfma_f32_16x16x32_bf16 v[16:19], v[180:183], v[220:223], v[16:19]
	v_mfma_f32_16x16x32_bf16 v[4:7], v[172:175], v[228:231], v[4:7]
	v_mfma_f32_16x16x32_bf16 v[0:3], v[180:183], v[228:231], v[0:3]
	v_mfma_f32_16x16x32_bf16 v[52:55], v[176:179], v[200:203], v[52:55]
	v_mfma_f32_16x16x32_bf16 v[48:51], v[184:187], v[200:203], v[48:51]
	v_mfma_f32_16x16x32_bf16 v[36:39], v[176:179], v[216:219], v[36:39]
	v_mfma_f32_16x16x32_bf16 v[32:35], v[184:187], v[216:219], v[32:35]
	v_mfma_f32_16x16x32_bf16 v[20:23], v[176:179], v[224:227], v[20:23]
	v_mfma_f32_16x16x32_bf16 v[16:19], v[184:187], v[224:227], v[16:19]
	v_mfma_f32_16x16x32_bf16 v[4:7], v[176:179], v[232:235], v[4:7]
	v_mfma_f32_16x16x32_bf16 v[0:3], v[184:187], v[232:235], v[0:3]
	s_barrier
	s_add_i32 s4, s4, 2
	s_add_u32 s36, s36, 0x800000
	s_addc_u32 s37, s37, 0
	s_add_u32 s38, s38, 0x100
	s_addc_u32 s39, s39, 0
	s_cmp_gt_u32 s4, 7
	s_cbranch_scc0 .LBB0_771
	s_setprio 0
	s_movk_i32 s0, 0x100
	v_cmp_gt_u32_e32 vcc, s0, v138
	s_and_saveexec_b64 s[0:1], vcc
	s_cbranch_execz .LBB0_774
	s_barrier

; #define LAS __attribute__((address_space(3)))
; #define WAIT_V(n) asm volatile("s_waitcnt vmcnt(" #n ")" ::: "memory")
; #define WAIT_L(n) asm volatile("s_waitcnt lgkmcnt(" #n ")" ::: "memory")
; #define BAR __builtin_amdgcn_s_barrier()
; #define SCHED __builtin_amdgcn_sched_barrier(0)
; #define STG_A(b, h, ptr) do { const char* _g = (ptr) + (h) * ahalf; LAS unsigned char* _l = lw + ((b) * 2 + (h)) * 16384; GLDS(_g + voa0, _l); GLDS(_g + voa1, _l + 8192); } while (0)
; #define STG_B(b, h, ptr) do { const char* _g = (ptr) + (h) * bhalf; LAS unsigned char* _l = lw + 65536 + ((b) * 2 + (h)) * 16384; GLDS(_g + vob0, _l); GLDS(_g + vob1, _l + 8192); } while (0)
; template <int BMODE, class Epi, class TileFn>
; DEV void gemm_loop(LAS unsigned char* lds, const bf16_t* __restrict__ A, int lda, const bf16_t* __restrict__ B, int ldb, int K, const Epi& epi, int t0, int tstep, int tend, const TileFn& tf) {
;     ...
;     if (BMODE == 0) { vob0 = (unsigned)(r0b * ldb + c0) * 2u; vob1 = vob0 + (unsigned)(64 * ldb) * 2u; bks = 128; bhalf = (size_t)128 * ldb * 2; }
;     else { vob0 = (unsigned)((c0 >> 3) * ldb + r0b) * 16u; vob1 = vob0 + 64u * 16u; bks = (size_t)ldb * 128; bhalf = 128 * 16; }
;     LAS unsigned char* lw = lds + tid * 16;
;     const int sw = swz_off(fr, fq);
;     LAS unsigned char* la = lds + wr * 8192 + sw;
;     LAS unsigned char* lb = lds + 65536 + wc * 4096 + sw;
;     int brow, bcol; tf(t0, brow, bcol);
;     const char* cA = (const char*)(A + (size_t)brow * lda);
;     const char* cB = BMODE == 0 ? (const char*)(B + (size_t)bcol * ldb) : (const char*)(B + (size_t)bcol * 8);
;     ...
;     const int nt = K / 64;
;     f32x4 acc[2][2][4][2];
; #pragma unroll
;     for (int a = 0; a < 2; ++a)
; #pragma unroll
;         for (int b = 0; b < 2; ++b)
; #pragma unroll
;             for (int m = 0; m < 4; ++m)
; #pragma unroll
;                 for (int n = 0; n < 2; ++n) acc[a][b][m][n] = (f32x4){0.f, 0.f, 0.f, 0.f};
;     bf16x8 At[4][2], B0[2][2], B1[2][2];
;     STG_B(0, 0, cB); STG_B(0, 1, cB); STG_A(0, 0, cA); STG_A(0, 1, cA);
;     if (wr == 1) BAR;
;     WAIT_V(2); BAR;
;     STG_B(1, 0, cB + bks); STG_A(1, 0, cA + 128); STG_B(1, 1, cB + bks);
;     WAIT_V(6); BAR;
;     ...
;             LDB(B0, 0, 0); LDB(B1, 0, 1); SCHED; LDA(At, 0, 0); STG_A(1, 1, a1);
;             WAIT_V(8); WAIT_L(0); BAR; MMA(0, 0, At, B0); MMA(0, 1, At, B1); BAR; SCHED;
.LBB0_811:
	s_or_b64 exec, exec, s[8:9]
	v_lshl_add_u32 v11, v8, 13, 0
	v_lshlrev_b32_e32 v8, 6, v138
	v_and_b32_e32 v8, 0x3000, v8
	s_add_i32 s8, 0, 0x10000
	v_add_u32_e32 v12, s8, v8
	s_bfe_u32 s8, s7, 0x20008
	v_and_b32_e32 v9, 15, v138
	v_lshlrev_b32_e32 v10, 2, v138
	s_mul_i32 s29, s8, 0x110000
	s_add_u32 s8, s0, 0x80000
	v_add_u32_e32 v147, 0x18000, v139
	v_lshlrev_b32_e32 v9, 6, v9
	v_and_b32_e32 v10, 32, v10
	v_and_b32_e32 v8, 48, v138
	s_addc_u32 s9, s1, 0
	v_readfirstlane_b32 s30, v147
	v_bitop3_b32 v10, v9, v10, v8 bitop3:0x36
	v_lshl_add_u64 v[8:9], s[8:9], 0, v[194:195]
	s_mov_b32 m0, s30
	v_add_u32_e32 v148, 0x1a000, v139
	s_waitcnt vmcnt(2)
	s_barrier
	global_load_lds_dwordx4 v[8:9], off
	v_lshl_add_u64 v[8:9], s[8:9], 0, v[132:133]
	v_readfirstlane_b32 s8, v148
	v_add_u32_e32 v149, 0x8000, v139
	s_mov_b32 m0, s8
	v_readfirstlane_b32 s8, v149
	v_add_u32_e32 v150, 0xa000, v139
	global_load_lds_dwordx4 v[8:9], off
	v_lshl_add_u64 v[2:3], v[2:3], 0, s[2:3]
	s_mov_b32 m0, s8
	v_readfirstlane_b32 s8, v150
	global_load_lds_dwordx4 v[2:3], off
	s_mov_b32 m0, s8
	s_add_u32 s8, s0, 0x80800
	v_add_u32_e32 v151, 0x1c000, v139
	v_lshl_add_u64 v[0:1], v[0:1], 0, s[2:3]
	s_addc_u32 s9, s1, 0
	v_readfirstlane_b32 s30, v151
	global_load_lds_dwordx4 v[0:1], off
	v_lshl_add_u64 v[0:1], s[8:9], 0, v[194:195]
	s_mov_b32 m0, s30
	v_add_u32_e32 v152, 0x1e000, v139
	global_load_lds_dwordx4 v[0:1], off
	v_lshl_add_u64 v[0:1], s[8:9], 0, v[132:133]
	v_readfirstlane_b32 s8, v152
	s_mov_b32 m0, s8
	s_mov_b32 s8, 0x8800
	global_load_lds_dwordx4 v[0:1], off
	v_lshrrev_b32_e32 v0, 4, v6
	v_mul_lo_u32 v0, v0, s8
	v_or_b32_e32 v0, v7, v0
	s_movk_i32 s8, 0x880
	v_mad_u32_u24 v0, v4, s8, v0
	s_add_u32 s8, s66, s29
	v_add_lshl_u32 v0, v0, v5, 1
	v_mov_b32_e32 v1, v195
	s_addc_u32 s9, s67, 0
	s_waitcnt vmcnt(6)
	v_lshl_add_u64 v[134:135], s[8:9], 0, v[0:1]
	v_add_u32_e32 v0, 0x44000, v0
	v_lshl_add_u64 v[136:137], s[8:9], 0, v[0:1]
	s_mov_b32 s29, -2
	s_mov_b64 s[38:39], 0x100000
	s_mov_b64 s[40:41], 0x5ad0080
	v_add_u32_e32 v153, v12, v10
	v_add_u32_e32 v154, v11, v10
	s_barrier
	v_readfirstlane_b32 s100, v188
	s_nop 3
	s_cmp_lt_u32 s100, 0x100
	s_cbranch_scc1 .Lsp_812
	s_setprio 1
.Lsp_812:
	ds_read_b128 v[156:159], v153
	ds_read_b128 v[160:163], v153 offset:1024
	ds_read_b128 v[164:167], v153 offset:2048
	ds_read_b128 v[168:171], v153 offset:3072
	ds_read_b128 v[172:175], v153 offset:16384
	ds_read_b128 v[176:179], v153 offset:17408
	ds_read_b128 v[180:183], v153 offset:18432
	ds_read_b128 v[184:187], v153 offset:19456
	s_add_u32 s8, s40, 0xfa530080
	s_addc_u32 s9, s41, -1
	s_cmp_eq_u32 s29, 30
	s_cselect_b32 s8, 0, s8
	s_cselect_b32 s9, 0, s9
	s_cselect_b32 s30, 0, s38
	s_cselect_b32 s31, 0, s39
	s_add_u32 s42, s36, s8
	s_addc_u32 s43, s37, s9
	s_add_u32 s8, s0, s30
	s_addc_u32 s9, s1, s31
	v_add_u32_e32 v155, 0xc000, v139
	v_lshl_add_u64 v[204:205], v[134:135], 0, s[40:41]
	v_readfirstlane_b32 s30, v155
	v_add_u32_e32 v155, 0xe000, v139
	s_mov_b32 m0, s30
	v_readfirstlane_b32 s30, v155
	ds_read_b128 v[196:199], v154
	ds_read_b128 v[200:203], v154 offset:1024
	ds_read_b128 v[212:215], v154 offset:2048
	ds_read_b128 v[216:219], v154 offset:3072
	ds_read_b128 v[220:223], v154 offset:4096
	ds_read_b128 v[224:227], v154 offset:5120
	ds_read_b128 v[228:231], v154 offset:6144
	ds_read_b128 v[232:235], v154 offset:7168
	global_load_lds_dwordx4 v[204:205], off
	v_lshl_add_u64 v[204:205], v[136:137], 0, s[40:41]
	s_mov_b32 m0, s30
	s_nop 0
	global_load_lds_dwordx4 v[204:205], off
	s_waitcnt vmcnt(8)
	s_waitcnt lgkmcnt(0)
	s_barrier
	s_waitcnt lgkmcnt(0)
	v_mfma_f32_16x16x32_bf16 v[124:127], v[156:159], v[196:199], 0
	v_mfma_f32_16x16x32_bf16 v[120:123], v[164:167], v[196:199], 0
	v_mfma_f32_16x16x32_bf16 v[108:111], v[156:159], v[212:215], 0
	v_mfma_f32_16x16x32_bf16 v[104:107], v[164:167], v[212:215], 0
	v_mfma_f32_16x16x32_bf16 v[92:95], v[156:159], v[220:223], 0
	v_mfma_f32_16x16x32_bf16 v[88:91], v[164:167], v[220:223], 0
	v_mfma_f32_16x16x32_bf16 v[76:79], v[156:159], v[228:231], 0
	v_mfma_f32_16x16x32_bf16 v[72:75], v[164:167], v[228:231], 0
	v_mfma_f32_16x16x32_bf16 v[124:127], v[160:163], v[200:203], v[124:127]
	v_mfma_f32_16x16x32_bf16 v[120:123], v[168:171], v[200:203], v[120:123]
	v_mfma_f32_16x16x32_bf16 v[108:111], v[160:163], v[216:219], v[108:111]
	v_mfma_f32_16x16x32_bf16 v[104:107], v[168:171], v[216:219], v[104:107]
	v_mfma_f32_16x16x32_bf16 v[92:95], v[160:163], v[224:227], v[92:95]
	v_mfma_f32_16x16x32_bf16 v[88:91], v[168:171], v[224:227], v[88:91]
	v_mfma_f32_16x16x32_bf16 v[76:79], v[160:163], v[232:235], v[76:79]
	v_mfma_f32_16x16x32_bf16 v[72:75], v[168:171], v[232:235], v[72:75]
	v_mfma_f32_16x16x32_bf16 v[116:119], v[172:175], v[196:199], 0
	v_mfma_f32_16x16x32_bf16 v[112:115], v[180:183], v[196:199], 0
	v_mfma_f32_16x16x32_bf16 v[100:103], v[172:175], v[212:215], 0
	v_mfma_f32_16x16x32_bf16 v[96:99], v[180:183], v[212:215], 0
	v_mfma_f32_16x16x32_bf16 v[84:87], v[172:175], v[220:223], 0
	v_mfma_f32_16x16x32_bf16 v[80:83], v[180:183], v[220:223], 0
	v_mfma_f32_16x16x32_bf16 v[68:71], v[172:175], v[228:231], 0
	v_mfma_f32_16x16x32_bf16 v[64:67], v[180:183], v[228:231], 0
	v_mfma_f32_16x16x32_bf16 v[116:119], v[176:179], v[200:203], v[116:119]
	v_mfma_f32_16x16x32_bf16 v[112:115], v[184:187], v[200:203], v[112:115]
	v_mfma_f32_16x16x32_bf16 v[100:103], v[176:179], v[216:219], v[100:103]
	v_mfma_f32_16x16x32_bf16 v[96:99], v[184:187], v[216:219], v[96:99]
	v_mfma_f32_16x16x32_bf16 v[84:87], v[176:179], v[224:227], v[84:87]
	v_mfma_f32_16x16x32_bf16 v[80:83], v[184:187], v[224:227], v[80:83]
	v_mfma_f32_16x16x32_bf16 v[68:71], v[176:179], v[232:235], v[68:71]
	v_mfma_f32_16x16x32_bf16 v[64:67], v[184:187], v[232:235], v[64:67]
	s_barrier
; #define WAIT_V(n) asm volatile("s_waitcnt vmcnt(" #n ")" ::: "memory")
; #define WAIT_L(n) asm volatile("s_waitcnt lgkmcnt(" #n ")" ::: "memory")
; #define BAR __builtin_amdgcn_s_barrier()
; #define SCHED __builtin_amdgcn_sched_barrier(0)
; #define STG_A(b, h, ptr) do { const char* _g = (ptr) + (h) * ahalf; LAS unsigned char* _l = lw + ((b) * 2 + (h)) * 16384; GLDS(_g + voa0, _l); GLDS(_g + voa1, _l + 8192); } while (0)
; #define STG_B(b, h, ptr) do { const char* _g = (ptr) + (h) * bhalf; LAS unsigned char* _l = lw + 65536 + ((b) * 2 + (h)) * 16384; GLDS(_g + vob0, _l); GLDS(_g + vob1, _l + 8192); } while (0)
; #define LDA(dst, b, h) _Pragma("unroll") for (int m = 0; m < 4; ++m) _Pragma("unroll") for (int k = 0; k < 2; ++k) dst[m][k] = *(const LAS bf16x8*)(la + ((b) * 2 + (h)) * 16384 + m * 2048 + k * 1024)
; #define LDB(dst, b, h) _Pragma("unroll") for (int n = 0; n < 2; ++n) _Pragma("unroll") for (int k = 0; k < 2; ++k) dst[n][k] = *(const LAS bf16x8*)(lb + ((b) * 2 + (h)) * 16384 + n * 2048 + k * 1024)
; #define MMA(ai, bj, Af, Bf) do { __builtin_amdgcn_s_setprio(1); \
;     _Pragma("unroll") for (int m = 0; m < 4; ++m) _Pragma("unroll") for (int n = 0; n < 2; ++n) _Pragma("unroll") for (int k = 0; k < 2; ++k) \
;         acc[ai][bj][m][n] = __builtin_amdgcn_mfma_f32_16x16x32_bf16(Bf[n][k], Af[m][k], acc[ai][bj][m][n], 0, 0, 0); \
;     __builtin_amdgcn_s_setprio(0); } while (0)
; template <int BMODE, class Epi, class TileFn>
; DEV void gemm_loop(LAS unsigned char* lds, const bf16_t* __restrict__ A, int lda, const bf16_t* __restrict__ B, int ldb, int K, const Epi& epi, int t0, int tstep, int tend, const TileFn& tf) {
;     ...
;             LDB(B0, 0, 0); LDB(B1, 0, 1); SCHED; LDA(At, 0, 0); STG_A(1, 1, a1);
;             WAIT_V(8); WAIT_L(0); BAR; MMA(0, 0, At, B0); MMA(0, 1, At, B1); BAR; SCHED;
;             LDA(At, 0, 1); STG_B(0, 0, b2); STG_B(0, 1, b2); STG_A(0, 0, a2);
;             WAIT_V(8); WAIT_L(0); BAR; MMA(1, 0, At, B0); MMA(1, 1, At, B1); BAR; SCHED;
	v_readfirstlane_b32 s30, v140
	v_lshl_add_u64 v[204:205], s[8:9], 0, v[194:195]
	s_mov_b32 m0, s30
	v_readfirstlane_b32 s30, v141
	ds_read_b128 v[196:199], v154 offset:16384
	ds_read_b128 v[200:203], v154 offset:17408
	ds_read_b128 v[212:215], v154 offset:18432
	ds_read_b128 v[216:219], v154 offset:19456
	ds_read_b128 v[220:223], v154 offset:20480
	ds_read_b128 v[224:227], v154 offset:21504
	ds_read_b128 v[228:231], v154 offset:22528
	ds_read_b128 v[232:235], v154 offset:23552
	global_load_lds_dwordx4 v[204:205], off
	v_lshl_add_u64 v[236:237], s[8:9], 0, v[132:133]
	s_mov_b32 m0, s30
	v_readfirstlane_b32 s30, v142
	global_load_lds_dwordx4 v[236:237], off
	v_lshl_add_u64 v[204:205], v[204:205], 0, s[86:87]
	s_mov_b32 m0, s30
	v_readfirstlane_b32 s30, v143
	global_load_lds_dwordx4 v[204:205], off
	v_lshl_add_u64 v[204:205], v[236:237], 0, s[86:87]
	s_mov_b32 m0, s30
	v_readfirstlane_b32 s30, v139
	global_load_lds_dwordx4 v[204:205], off
	v_lshl_add_u64 v[204:205], s[42:43], 0, v[128:129]
	s_mov_b32 m0, s30
	v_readfirstlane_b32 s30, v144
	global_load_lds_dwordx4 v[204:205], off
	v_lshl_add_u64 v[236:237], s[42:43], 0, v[130:131]
	s_mov_b32 m0, s30
	s_nop 0
	global_load_lds_dwordx4 v[236:237], off
	s_waitcnt vmcnt(8)
	s_waitcnt lgkmcnt(0)
	s_barrier
	s_waitcnt lgkmcnt(0)
	v_mfma_f32_16x16x32_bf16 v[60:63], v[156:159], v[196:199], 0
	v_mfma_f32_16x16x32_bf16 v[56:59], v[164:167], v[196:199], 0
	v_mfma_f32_16x16x32_bf16 v[44:47], v[156:159], v[212:215], 0
	v_mfma_f32_16x16x32_bf16 v[40:43], v[164:167], v[212:215], 0
	v_mfma_f32_16x16x32_bf16 v[28:31], v[156:159], v[220:223], 0
	v_mfma_f32_16x16x32_bf16 v[24:27], v[164:167], v[220:223], 0
	v_mfma_f32_16x16x32_bf16 v[12:15], v[156:159], v[228:231], 0
	v_mfma_f32_16x16x32_bf16 v[8:11], v[164:167], v[228:231], 0
	v_mfma_f32_16x16x32_bf16 v[60:63], v[160:163], v[200:203], v[60:63]
	v_mfma_f32_16x16x32_bf16 v[56:59], v[168:171], v[200:203], v[56:59]
	v_mfma_f32_16x16x32_bf16 v[44:47], v[160:163], v[216:219], v[44:47]
	v_mfma_f32_16x16x32_bf16 v[40:43], v[168:171], v[216:219], v[40:43]
	v_mfma_f32_16x16x32_bf16 v[28:31], v[160:163], v[224:227], v[28:31]
	v_mfma_f32_16x16x32_bf16 v[24:27], v[168:171], v[224:227], v[24:27]
	v_mfma_f32_16x16x32_bf16 v[12:15], v[160:163], v[232:235], v[12:15]
	v_mfma_f32_16x16x32_bf16 v[8:11], v[168:171], v[232:235], v[8:11]
	v_mfma_f32_16x16x32_bf16 v[52:55], v[172:175], v[196:199], 0
	v_mfma_f32_16x16x32_bf16 v[48:51], v[180:183], v[196:199], 0
	v_mfma_f32_16x16x32_bf16 v[36:39], v[172:175], v[212:215], 0
	v_mfma_f32_16x16x32_bf16 v[32:35], v[180:183], v[212:215], 0
	v_mfma_f32_16x16x32_bf16 v[20:23], v[172:175], v[220:223], 0
	v_mfma_f32_16x16x32_bf16 v[16:19], v[180:183], v[220:223], 0
	v_mfma_f32_16x16x32_bf16 v[4:7], v[172:175], v[228:231], 0
	v_mfma_f32_16x16x32_bf16 v[0:3], v[180:183], v[228:231], 0
	v_mfma_f32_16x16x32_bf16 v[52:55], v[176:179], v[200:203], v[52:55]
	v_mfma_f32_16x16x32_bf16 v[48:51], v[184:187], v[200:203], v[48:51]
	v_mfma_f32_16x16x32_bf16 v[36:39], v[176:179], v[216:219], v[36:39]
	v_mfma_f32_16x16x32_bf16 v[32:35], v[184:187], v[216:219], v[32:35]
	v_mfma_f32_16x16x32_bf16 v[20:23], v[176:179], v[224:227], v[20:23]
	v_mfma_f32_16x16x32_bf16 v[16:19], v[184:187], v[224:227], v[16:19]
	v_mfma_f32_16x16x32_bf16 v[4:7], v[176:179], v[232:235], v[4:7]
	v_mfma_f32_16x16x32_bf16 v[0:3], v[184:187], v[232:235], v[0:3]
	s_barrier
	s_branch .Lkmid_812
.LBB0_812:
	ds_read_b128 v[156:159], v153
	ds_read_b128 v[160:163], v153 offset:1024
	ds_read_b128 v[164:167], v153 offset:2048
	ds_read_b128 v[168:171], v153 offset:3072
	ds_read_b128 v[172:175], v153 offset:16384
	ds_read_b128 v[176:179], v153 offset:17408
	ds_read_b128 v[180:183], v153 offset:18432
	ds_read_b128 v[184:187], v153 offset:19456
	s_add_u32 s8, s40, 0xfa530080
	s_addc_u32 s9, s41, -1
	s_cmp_eq_u32 s29, 30
	s_cselect_b32 s8, 0, s8
	s_cselect_b32 s9, 0, s9
	s_cselect_b32 s30, 0, s38
	s_cselect_b32 s31, 0, s39
	s_add_u32 s42, s36, s8
	s_addc_u32 s43, s37, s9
	s_add_u32 s8, s0, s30
	s_addc_u32 s9, s1, s31
	v_add_u32_e32 v155, 0xc000, v139
	v_lshl_add_u64 v[204:205], v[134:135], 0, s[40:41]
	v_readfirstlane_b32 s30, v155
	v_add_u32_e32 v155, 0xe000, v139
	s_mov_b32 m0, s30
	v_readfirstlane_b32 s30, v155
	ds_read_b128 v[196:199], v154
	ds_read_b128 v[200:203], v154 offset:1024
	ds_read_b128 v[212:215], v154 offset:2048
	ds_read_b128 v[216:219], v154 offset:3072
	ds_read_b128 v[220:223], v154 offset:4096
	ds_read_b128 v[224:227], v154 offset:5120
	ds_read_b128 v[228:231], v154 offset:6144
	ds_read_b128 v[232:235], v154 offset:7168
	global_load_lds_dwordx4 v[204:205], off
	v_lshl_add_u64 v[204:205], v[136:137], 0, s[40:41]
	s_mov_b32 m0, s30
	s_nop 0
	global_load_lds_dwordx4 v[204:205], off
	s_waitcnt vmcnt(8)
	s_waitcnt lgkmcnt(0)
	s_barrier
; #define WAIT_V(n) asm volatile("s_waitcnt vmcnt(" #n ")" ::: "memory")
; #define WAIT_L(n) asm volatile("s_waitcnt lgkmcnt(" #n ")" ::: "memory")
; #define BAR __builtin_amdgcn_s_barrier()
; #define SCHED __builtin_amdgcn_sched_barrier(0)
; #define STG_A(b, h, ptr) do { const char* _g = (ptr) + (h) * ahalf; LAS unsigned char* _l = lw + ((b) * 2 + (h)) * 16384; GLDS(_g + voa0, _l); GLDS(_g + voa1, _l + 8192); } while (0)
; #define STG_B(b, h, ptr) do { const char* _g = (ptr) + (h) * bhalf; LAS unsigned char* _l = lw + 65536 + ((b) * 2 + (h)) * 16384; GLDS(_g + vob0, _l); GLDS(_g + vob1, _l + 8192); } while (0)
; #define LDA(dst, b, h) _Pragma("unroll") for (int m = 0; m < 4; ++m) _Pragma("unroll") for (int k = 0; k < 2; ++k) dst[m][k] = *(const LAS bf16x8*)(la + ((b) * 2 + (h)) * 16384 + m * 2048 + k * 1024)
; #define MMA(ai, bj, Af, Bf) do { __builtin_amdgcn_s_setprio(1); \
;     _Pragma("unroll") for (int m = 0; m < 4; ++m) _Pragma("unroll") for (int n = 0; n < 2; ++n) _Pragma("unroll") for (int k = 0; k < 2; ++k) \
;         acc[ai][bj][m][n] = __builtin_amdgcn_mfma_f32_16x16x32_bf16(Bf[n][k], Af[m][k], acc[ai][bj][m][n], 0, 0, 0); \
;     __builtin_amdgcn_s_setprio(0); } while (0)
; template <int BMODE, class Epi, class TileFn>
; DEV void gemm_loop(LAS unsigned char* lds, const bf16_t* __restrict__ A, int lda, const bf16_t* __restrict__ B, int ldb, int K, const Epi& epi, int t0, int tstep, int tend, const TileFn& tf) {
;     ...
;             WAIT_V(8); WAIT_L(0); BAR; MMA(0, 0, At, B0); MMA(0, 1, At, B1); BAR; SCHED;
;             LDA(At, 0, 1); STG_B(0, 0, b2); STG_B(0, 1, b2); STG_A(0, 0, a2);
;             WAIT_V(8); WAIT_L(0); BAR; MMA(1, 0, At, B0); MMA(1, 1, At, B1); BAR; SCHED;
	s_waitcnt lgkmcnt(0)
	v_mfma_f32_16x16x32_bf16 v[124:127], v[156:159], v[196:199], v[124:127]
	v_mfma_f32_16x16x32_bf16 v[120:123], v[164:167], v[196:199], v[120:123]
	v_mfma_f32_16x16x32_bf16 v[108:111], v[156:159], v[212:215], v[108:111]
	v_mfma_f32_16x16x32_bf16 v[104:107], v[164:167], v[212:215], v[104:107]
	v_mfma_f32_16x16x32_bf16 v[92:95], v[156:159], v[220:223], v[92:95]
	v_mfma_f32_16x16x32_bf16 v[88:91], v[164:167], v[220:223], v[88:91]
	v_mfma_f32_16x16x32_bf16 v[76:79], v[156:159], v[228:231], v[76:79]
	v_mfma_f32_16x16x32_bf16 v[72:75], v[164:167], v[228:231], v[72:75]
	v_mfma_f32_16x16x32_bf16 v[124:127], v[160:163], v[200:203], v[124:127]
	v_mfma_f32_16x16x32_bf16 v[120:123], v[168:171], v[200:203], v[120:123]
	v_mfma_f32_16x16x32_bf16 v[108:111], v[160:163], v[216:219], v[108:111]
	v_mfma_f32_16x16x32_bf16 v[104:107], v[168:171], v[216:219], v[104:107]
	v_mfma_f32_16x16x32_bf16 v[92:95], v[160:163], v[224:227], v[92:95]
	v_mfma_f32_16x16x32_bf16 v[88:91], v[168:171], v[224:227], v[88:91]
	v_mfma_f32_16x16x32_bf16 v[76:79], v[160:163], v[232:235], v[76:79]
	v_mfma_f32_16x16x32_bf16 v[72:75], v[168:171], v[232:235], v[72:75]
	v_mfma_f32_16x16x32_bf16 v[116:119], v[172:175], v[196:199], v[116:119]
	v_mfma_f32_16x16x32_bf16 v[112:115], v[180:183], v[196:199], v[112:115]
	v_mfma_f32_16x16x32_bf16 v[100:103], v[172:175], v[212:215], v[100:103]
	v_mfma_f32_16x16x32_bf16 v[96:99], v[180:183], v[212:215], v[96:99]
	v_mfma_f32_16x16x32_bf16 v[84:87], v[172:175], v[220:223], v[84:87]
	v_mfma_f32_16x16x32_bf16 v[80:83], v[180:183], v[220:223], v[80:83]
	v_mfma_f32_16x16x32_bf16 v[68:71], v[172:175], v[228:231], v[68:71]
	v_mfma_f32_16x16x32_bf16 v[64:67], v[180:183], v[228:231], v[64:67]
	v_mfma_f32_16x16x32_bf16 v[116:119], v[176:179], v[200:203], v[116:119]
	v_mfma_f32_16x16x32_bf16 v[112:115], v[184:187], v[200:203], v[112:115]
	v_mfma_f32_16x16x32_bf16 v[100:103], v[176:179], v[216:219], v[100:103]
	v_mfma_f32_16x16x32_bf16 v[96:99], v[184:187], v[216:219], v[96:99]
	v_mfma_f32_16x16x32_bf16 v[84:87], v[176:179], v[224:227], v[84:87]
	v_mfma_f32_16x16x32_bf16 v[80:83], v[184:187], v[224:227], v[80:83]
	v_mfma_f32_16x16x32_bf16 v[68:71], v[176:179], v[232:235], v[68:71]
	v_mfma_f32_16x16x32_bf16 v[64:67], v[184:187], v[232:235], v[64:67]
	s_barrier
	v_readfirstlane_b32 s30, v140
	v_lshl_add_u64 v[204:205], s[8:9], 0, v[194:195]
	s_mov_b32 m0, s30
	v_readfirstlane_b32 s30, v141
	ds_read_b128 v[196:199], v154 offset:16384
	ds_read_b128 v[200:203], v154 offset:17408
	ds_read_b128 v[212:215], v154 offset:18432
	ds_read_b128 v[216:219], v154 offset:19456
	ds_read_b128 v[220:223], v154 offset:20480
	ds_read_b128 v[224:227], v154 offset:21504
	ds_read_b128 v[228:231], v154 offset:22528
	ds_read_b128 v[232:235], v154 offset:23552
	global_load_lds_dwordx4 v[204:205], off
	v_lshl_add_u64 v[236:237], s[8:9], 0, v[132:133]
	s_mov_b32 m0, s30
	v_readfirstlane_b32 s30, v142
	global_load_lds_dwordx4 v[236:237], off
	v_lshl_add_u64 v[204:205], v[204:205], 0, s[86:87]
	s_mov_b32 m0, s30
	v_readfirstlane_b32 s30, v143
	global_load_lds_dwordx4 v[204:205], off
	v_lshl_add_u64 v[204:205], v[236:237], 0, s[86:87]
	s_mov_b32 m0, s30
	v_readfirstlane_b32 s30, v139
	global_load_lds_dwordx4 v[204:205], off
	v_lshl_add_u64 v[204:205], s[42:43], 0, v[128:129]
	s_mov_b32 m0, s30
	v_readfirstlane_b32 s30, v144
	global_load_lds_dwordx4 v[204:205], off
	v_lshl_add_u64 v[236:237], s[42:43], 0, v[130:131]
	s_mov_b32 m0, s30
	s_nop 0
	global_load_lds_dwordx4 v[236:237], off
	s_waitcnt vmcnt(8)
	s_waitcnt lgkmcnt(0)
	s_barrier
	s_waitcnt lgkmcnt(0)
	v_mfma_f32_16x16x32_bf16 v[60:63], v[156:159], v[196:199], v[60:63]
	v_mfma_f32_16x16x32_bf16 v[56:59], v[164:167], v[196:199], v[56:59]
	v_mfma_f32_16x16x32_bf16 v[44:47], v[156:159], v[212:215], v[44:47]
	v_mfma_f32_16x16x32_bf16 v[40:43], v[164:167], v[212:215], v[40:43]
	v_mfma_f32_16x16x32_bf16 v[28:31], v[156:159], v[220:223], v[28:31]
	v_mfma_f32_16x16x32_bf16 v[24:27], v[164:167], v[220:223], v[24:27]
	v_mfma_f32_16x16x32_bf16 v[12:15], v[156:159], v[228:231], v[12:15]
	v_mfma_f32_16x16x32_bf16 v[8:11], v[164:167], v[228:231], v[8:11]
	v_mfma_f32_16x16x32_bf16 v[60:63], v[160:163], v[200:203], v[60:63]
	v_mfma_f32_16x16x32_bf16 v[56:59], v[168:171], v[200:203], v[56:59]
	v_mfma_f32_16x16x32_bf16 v[44:47], v[160:163], v[216:219], v[44:47]
	v_mfma_f32_16x16x32_bf16 v[40:43], v[168:171], v[216:219], v[40:43]
	v_mfma_f32_16x16x32_bf16 v[28:31], v[160:163], v[224:227], v[28:31]
	v_mfma_f32_16x16x32_bf16 v[24:27], v[168:171], v[224:227], v[24:27]
	v_mfma_f32_16x16x32_bf16 v[12:15], v[160:163], v[232:235], v[12:15]
	v_mfma_f32_16x16x32_bf16 v[8:11], v[168:171], v[232:235], v[8:11]
	v_mfma_f32_16x16x32_bf16 v[52:55], v[172:175], v[196:199], v[52:55]
	v_mfma_f32_16x16x32_bf16 v[48:51], v[180:183], v[196:199], v[48:51]
	v_mfma_f32_16x16x32_bf16 v[36:39], v[172:175], v[212:215], v[36:39]
	v_mfma_f32_16x16x32_bf16 v[32:35], v[180:183], v[212:215], v[32:35]
	v_mfma_f32_16x16x32_bf16 v[20:23], v[172:175], v[220:223], v[20:23]
	v_mfma_f32_16x16x32_bf16 v[16:19], v[180:183], v[220:223], v[16:19]
	v_mfma_f32_16x16x32_bf16 v[4:7], v[172:175], v[228:231], v[4:7]
	v_mfma_f32_16x16x32_bf16 v[0:3], v[180:183], v[228:231], v[0:3]
	v_mfma_f32_16x16x32_bf16 v[52:55], v[176:179], v[200:203], v[52:55]
	v_mfma_f32_16x16x32_bf16 v[48:51], v[184:187], v[200:203], v[48:51]
	v_mfma_f32_16x16x32_bf16 v[36:39], v[176:179], v[216:219], v[36:39]
	v_mfma_f32_16x16x32_bf16 v[32:35], v[184:187], v[216:219], v[32:35]
	v_mfma_f32_16x16x32_bf16 v[20:23], v[176:179], v[224:227], v[20:23]
	v_mfma_f32_16x16x32_bf16 v[16:19], v[184:187], v[224:227], v[16:19]
	v_mfma_f32_16x16x32_bf16 v[4:7], v[176:179], v[232:235], v[4:7]
	v_mfma_f32_16x16x32_bf16 v[0:3], v[184:187], v[232:235], v[0:3]
	s_barrier
; #define WAIT_V(n) asm volatile("s_waitcnt vmcnt(" #n ")" ::: "memory")
; #define WAIT_L(n) asm volatile("s_waitcnt lgkmcnt(" #n ")" ::: "memory")
; #define BAR __builtin_amdgcn_s_barrier()
; #define SCHED __builtin_amdgcn_sched_barrier(0)
; #define STG_A(b, h, ptr) do { const char* _g = (ptr) + (h) * ahalf; LAS unsigned char* _l = lw + ((b) * 2 + (h)) * 16384; GLDS(_g + voa0, _l); GLDS(_g + voa1, _l + 8192); } while (0)
; #define LDA(dst, b, h) _Pragma("unroll") for (int m = 0; m < 4; ++m) _Pragma("unroll") for (int k = 0; k < 2; ++k) dst[m][k] = *(const LAS bf16x8*)(la + ((b) * 2 + (h)) * 16384 + m * 2048 + k * 1024)
; #define LDB(dst, b, h) _Pragma("unroll") for (int n = 0; n < 2; ++n) _Pragma("unroll") for (int k = 0; k < 2; ++k) dst[n][k] = *(const LAS bf16x8*)(lb + ((b) * 2 + (h)) * 16384 + n * 2048 + k * 1024)
; #define MMA(ai, bj, Af, Bf) do { __builtin_amdgcn_s_setprio(1); \
;     _Pragma("unroll") for (int m = 0; m < 4; ++m) _Pragma("unroll") for (int n = 0; n < 2; ++n) _Pragma("unroll") for (int k = 0; k < 2; ++k) \
;         acc[ai][bj][m][n] = __builtin_amdgcn_mfma_f32_16x16x32_bf16(Bf[n][k], Af[m][k], acc[ai][bj][m][n], 0, 0, 0); \
;     __builtin_amdgcn_s_setprio(0); } while (0)
; template <int BMODE, class Epi, class TileFn>
; DEV void gemm_loop(LAS unsigned char* lds, const bf16_t* __restrict__ A, int lda, const bf16_t* __restrict__ B, int ldb, int K, const Epi& epi, int t0, int tstep, int tend, const TileFn& tf) {
;     ...
;             LDB(B0, 1, 0); LDB(B1, 1, 1); SCHED; LDA(At, 1, 0); STG_A(0, 1, a2);
;             WAIT_V(8); WAIT_L(0); BAR; MMA(0, 0, At, B0); MMA(0, 1, At, B1); BAR; SCHED;
.Lkmid_812:
	ds_read_b128 v[156:159], v153 offset:32768
	ds_read_b128 v[160:163], v153 offset:33792
	ds_read_b128 v[164:167], v153 offset:34816
	ds_read_b128 v[168:171], v153 offset:35840
	ds_read_b128 v[172:175], v153 offset:49152
	ds_read_b128 v[176:179], v153 offset:50176
	ds_read_b128 v[180:183], v153 offset:51200
	ds_read_b128 v[184:187], v153 offset:52224
	s_add_u32 s30, s42, 0x88000
	s_addc_u32 s31, s43, 0
	v_readfirstlane_b32 s42, v145
	v_lshl_add_u64 v[238:239], s[30:31], 0, v[128:129]
	s_mov_b32 m0, s42
	ds_read_b128 v[196:199], v154 offset:32768
	ds_read_b128 v[200:203], v154 offset:33792
	ds_read_b128 v[212:215], v154 offset:34816
	ds_read_b128 v[216:219], v154 offset:35840
	ds_read_b128 v[220:223], v154 offset:36864
	ds_read_b128 v[224:227], v154 offset:37888
	ds_read_b128 v[228:231], v154 offset:38912
	ds_read_b128 v[232:235], v154 offset:39936
	global_load_lds_dwordx4 v[238:239], off
	v_lshl_add_u64 v[238:239], s[30:31], 0, v[130:131]
	v_readfirstlane_b32 s30, v146
	s_mov_b32 m0, s30
	s_nop 0
	global_load_lds_dwordx4 v[238:239], off
	s_waitcnt vmcnt(8)
	s_waitcnt lgkmcnt(0)
	s_barrier
	s_waitcnt lgkmcnt(0)
	v_mfma_f32_16x16x32_bf16 v[124:127], v[156:159], v[196:199], v[124:127]
	v_mfma_f32_16x16x32_bf16 v[120:123], v[164:167], v[196:199], v[120:123]
	v_mfma_f32_16x16x32_bf16 v[108:111], v[156:159], v[212:215], v[108:111]
	v_mfma_f32_16x16x32_bf16 v[104:107], v[164:167], v[212:215], v[104:107]
	v_mfma_f32_16x16x32_bf16 v[92:95], v[156:159], v[220:223], v[92:95]
	v_mfma_f32_16x16x32_bf16 v[88:91], v[164:167], v[220:223], v[88:91]
	v_mfma_f32_16x16x32_bf16 v[76:79], v[156:159], v[228:231], v[76:79]
	v_mfma_f32_16x16x32_bf16 v[72:75], v[164:167], v[228:231], v[72:75]
	v_mfma_f32_16x16x32_bf16 v[124:127], v[160:163], v[200:203], v[124:127]
	v_mfma_f32_16x16x32_bf16 v[120:123], v[168:171], v[200:203], v[120:123]
	v_mfma_f32_16x16x32_bf16 v[108:111], v[160:163], v[216:219], v[108:111]
	v_mfma_f32_16x16x32_bf16 v[104:107], v[168:171], v[216:219], v[104:107]
	v_mfma_f32_16x16x32_bf16 v[92:95], v[160:163], v[224:227], v[92:95]
	v_mfma_f32_16x16x32_bf16 v[88:91], v[168:171], v[224:227], v[88:91]
	v_mfma_f32_16x16x32_bf16 v[76:79], v[160:163], v[232:235], v[76:79]
	v_mfma_f32_16x16x32_bf16 v[72:75], v[168:171], v[232:235], v[72:75]
	v_mfma_f32_16x16x32_bf16 v[116:119], v[172:175], v[196:199], v[116:119]
	v_mfma_f32_16x16x32_bf16 v[112:115], v[180:183], v[196:199], v[112:115]
	v_mfma_f32_16x16x32_bf16 v[100:103], v[172:175], v[212:215], v[100:103]
	v_mfma_f32_16x16x32_bf16 v[96:99], v[180:183], v[212:215], v[96:99]
	v_mfma_f32_16x16x32_bf16 v[84:87], v[172:175], v[220:223], v[84:87]
	v_mfma_f32_16x16x32_bf16 v[80:83], v[180:183], v[220:223], v[80:83]
	v_mfma_f32_16x16x32_bf16 v[68:71], v[172:175], v[228:231], v[68:71]
	v_mfma_f32_16x16x32_bf16 v[64:67], v[180:183], v[228:231], v[64:67]
	v_mfma_f32_16x16x32_bf16 v[116:119], v[176:179], v[200:203], v[116:119]
	v_mfma_f32_16x16x32_bf16 v[112:115], v[184:187], v[200:203], v[112:115]
	v_mfma_f32_16x16x32_bf16 v[100:103], v[176:179], v[216:219], v[100:103]
	v_mfma_f32_16x16x32_bf16 v[96:99], v[184:187], v[216:219], v[96:99]
	v_mfma_f32_16x16x32_bf16 v[84:87], v[176:179], v[224:227], v[84:87]
	v_mfma_f32_16x16x32_bf16 v[80:83], v[184:187], v[224:227], v[80:83]
	v_mfma_f32_16x16x32_bf16 v[68:71], v[176:179], v[232:235], v[68:71]
	v_mfma_f32_16x16x32_bf16 v[64:67], v[184:187], v[232:235], v[64:67]
	s_barrier
; #define WAIT_V(n) asm volatile("s_waitcnt vmcnt(" #n ")" ::: "memory")
; #define WAIT_L(n) asm volatile("s_waitcnt lgkmcnt(" #n ")" ::: "memory")
; #define BAR __builtin_amdgcn_s_barrier()
; #define SCHED __builtin_amdgcn_sched_barrier(0)
; #define STG_A(b, h, ptr) do { const char* _g = (ptr) + (h) * ahalf; LAS unsigned char* _l = lw + ((b) * 2 + (h)) * 16384; GLDS(_g + voa0, _l); GLDS(_g + voa1, _l + 8192); } while (0)
; #define STG_B(b, h, ptr) do { const char* _g = (ptr) + (h) * bhalf; LAS unsigned char* _l = lw + 65536 + ((b) * 2 + (h)) * 16384; GLDS(_g + vob0, _l); GLDS(_g + vob1, _l + 8192); } while (0)
; #define LDA(dst, b, h) _Pragma("unroll") for (int m = 0; m < 4; ++m) _Pragma("unroll") for (int k = 0; k < 2; ++k) dst[m][k] = *(const LAS bf16x8*)(la + ((b) * 2 + (h)) * 16384 + m * 2048 + k * 1024)
; #define MMA(ai, bj, Af, Bf) do { __builtin_amdgcn_s_setprio(1); \
;     _Pragma("unroll") for (int m = 0; m < 4; ++m) _Pragma("unroll") for (int n = 0; n < 2; ++n) _Pragma("unroll") for (int k = 0; k < 2; ++k) \
;         acc[ai][bj][m][n] = __builtin_amdgcn_mfma_f32_16x16x32_bf16(Bf[n][k], Af[m][k], acc[ai][bj][m][n], 0, 0, 0); \
;     __builtin_amdgcn_s_setprio(0); } while (0)
; template <int BMODE, class Epi, class TileFn>
; DEV void gemm_loop(LAS unsigned char* lds, const bf16_t* __restrict__ A, int lda, const bf16_t* __restrict__ B, int ldb, int K, const Epi& epi, int t0, int tstep, int tend, const TileFn& tf) {
;     ...
;             LDA(At, 1, 1); STG_B(1, 0, b3); STG_B(1, 1, b3); STG_A(1, 0, a3);
;             WAIT_V(8); WAIT_L(0); BAR; MMA(1, 0, At, B0); MMA(1, 1, At, B1); BAR; SCHED;
;         }
;         if (wr == 0) BAR;
	s_add_u32 s30, s8, 0x80000
	s_addc_u32 s31, s9, 0
	v_readfirstlane_b32 s42, v147
	v_lshl_add_u64 v[238:239], s[30:31], 0, v[194:195]
	s_mov_b32 m0, s42
	ds_read_b128 v[196:199], v154 offset:49152
	ds_read_b128 v[200:203], v154 offset:50176
	ds_read_b128 v[212:215], v154 offset:51200
	ds_read_b128 v[216:219], v154 offset:52224
	ds_read_b128 v[220:223], v154 offset:53248
	ds_read_b128 v[224:227], v154 offset:54272
	ds_read_b128 v[228:231], v154 offset:55296
	ds_read_b128 v[232:235], v154 offset:56320
	global_load_lds_dwordx4 v[238:239], off
	v_lshl_add_u64 v[238:239], s[30:31], 0, v[132:133]
	v_readfirstlane_b32 s30, v148
	s_add_u32 s8, s8, 0x80800
	s_mov_b32 m0, s30
	s_addc_u32 s9, s9, 0
	v_readfirstlane_b32 s30, v151
	global_load_lds_dwordx4 v[238:239], off
	v_lshl_add_u64 v[238:239], s[8:9], 0, v[194:195]
	s_mov_b32 m0, s30
	v_lshl_add_u64 v[204:205], v[204:205], 0, s[2:3]
	global_load_lds_dwordx4 v[238:239], off
	v_lshl_add_u64 v[238:239], s[8:9], 0, v[132:133]
	v_readfirstlane_b32 s8, v152
	s_mov_b32 m0, s8
	v_readfirstlane_b32 s8, v149
	global_load_lds_dwordx4 v[238:239], off
	s_mov_b32 m0, s8
	v_readfirstlane_b32 s8, v150
	global_load_lds_dwordx4 v[204:205], off
	v_lshl_add_u64 v[204:205], v[236:237], 0, s[2:3]
	s_mov_b32 m0, s8
	s_nop 0
	global_load_lds_dwordx4 v[204:205], off
	s_waitcnt vmcnt(8)
	s_waitcnt lgkmcnt(0)
	s_barrier
	s_waitcnt lgkmcnt(0)
	v_mfma_f32_16x16x32_bf16 v[60:63], v[156:159], v[196:199], v[60:63]
	v_mfma_f32_16x16x32_bf16 v[56:59], v[164:167], v[196:199], v[56:59]
	v_mfma_f32_16x16x32_bf16 v[44:47], v[156:159], v[212:215], v[44:47]
	v_mfma_f32_16x16x32_bf16 v[40:43], v[164:167], v[212:215], v[40:43]
	v_mfma_f32_16x16x32_bf16 v[28:31], v[156:159], v[220:223], v[28:31]
	v_mfma_f32_16x16x32_bf16 v[24:27], v[164:167], v[220:223], v[24:27]
	v_mfma_f32_16x16x32_bf16 v[12:15], v[156:159], v[228:231], v[12:15]
	v_mfma_f32_16x16x32_bf16 v[8:11], v[164:167], v[228:231], v[8:11]
	v_mfma_f32_16x16x32_bf16 v[60:63], v[160:163], v[200:203], v[60:63]
	v_mfma_f32_16x16x32_bf16 v[56:59], v[168:171], v[200:203], v[56:59]
	v_mfma_f32_16x16x32_bf16 v[44:47], v[160:163], v[216:219], v[44:47]
	v_mfma_f32_16x16x32_bf16 v[40:43], v[168:171], v[216:219], v[40:43]
	v_mfma_f32_16x16x32_bf16 v[28:31], v[160:163], v[224:227], v[28:31]
	v_mfma_f32_16x16x32_bf16 v[24:27], v[168:171], v[224:227], v[24:27]
	v_mfma_f32_16x16x32_bf16 v[12:15], v[160:163], v[232:235], v[12:15]
	v_mfma_f32_16x16x32_bf16 v[8:11], v[168:171], v[232:235], v[8:11]
	v_mfma_f32_16x16x32_bf16 v[52:55], v[172:175], v[196:199], v[52:55]
	v_mfma_f32_16x16x32_bf16 v[48:51], v[180:183], v[196:199], v[48:51]
	v_mfma_f32_16x16x32_bf16 v[36:39], v[172:175], v[212:215], v[36:39]
	v_mfma_f32_16x16x32_bf16 v[32:35], v[180:183], v[212:215], v[32:35]
	v_mfma_f32_16x16x32_bf16 v[20:23], v[172:175], v[220:223], v[20:23]
	v_mfma_f32_16x16x32_bf16 v[16:19], v[180:183], v[220:223], v[16:19]
	v_mfma_f32_16x16x32_bf16 v[4:7], v[172:175], v[228:231], v[4:7]
	v_mfma_f32_16x16x32_bf16 v[0:3], v[180:183], v[228:231], v[0:3]
	v_mfma_f32_16x16x32_bf16 v[52:55], v[176:179], v[200:203], v[52:55]
	v_mfma_f32_16x16x32_bf16 v[48:51], v[184:187], v[200:203], v[48:51]
	v_mfma_f32_16x16x32_bf16 v[36:39], v[176:179], v[216:219], v[36:39]
	v_mfma_f32_16x16x32_bf16 v[32:35], v[184:187], v[216:219], v[32:35]
	v_mfma_f32_16x16x32_bf16 v[20:23], v[176:179], v[224:227], v[20:23]
	v_mfma_f32_16x16x32_bf16 v[16:19], v[184:187], v[224:227], v[16:19]
	v_mfma_f32_16x16x32_bf16 v[4:7], v[176:179], v[232:235], v[4:7]
	v_mfma_f32_16x16x32_bf16 v[0:3], v[184:187], v[232:235], v[0:3]
	s_barrier
	s_add_i32 s29, s29, 2
	s_add_u32 s38, s38, 0x100000
	s_addc_u32 s39, s39, 0
	s_add_u32 s40, s40, 0x100
	s_addc_u32 s41, s41, 0
	s_cmp_gt_u32 s29, 31
	s_cbranch_scc0 .LBB0_812
	s_setprio 0
	s_movk_i32 s0, 0x100
	v_cmp_gt_u32_e32 vcc, s0, v138
	s_and_saveexec_b64 s[0:1], vcc
	s_cbranch_execz .LBB0_815
	s_barrier
